# combined: Vt-epilogue scale loads hoisted, LN row statistics read once per thread in the residual+LN epilogue, rope/retention table generation moved to workgroups with a single modulation task
# speedup vs baseline: 1.0093x; 1.0093x over previous
; #define otid() otid_impl(w0)
; __device__ __forceinline__ void sincos_d(double ang, float& c, float& s) {
;   const double TWO_PI = 6.283185307179586476925;
;   const double n = rint(ang / TWO_PI); const double r = ang - n * TWO_PI, r2 = r * r;
;   double tc = 1.0, sc = 1.0, ts = r, ss = r;
;   for (int k = 1; k <= 16; ++k) { tc *= -r2 / (double)((2 * k - 1) * (2 * k)); sc += tc; ts *= -r2 / (double)((2 * k) * (2 * k + 1)); ss += ts; }
; __device__ void table_phase(const Params& p, int w0) {
;   const int g = blockIdx.x * NTHREADS + otid();
;   if (g < 2048 * 8) {
;     const int t = g >> 3, i = g & 7; float c, s;
;     sincos_d((double)(t >> 6) * p.ax_inv[i], c, s); p.ropetab[t * 32 + i] = c; p.ropetab[t * 32 + 8 + i] = s;
;     sincos_d((double)(t & 63) * p.ax_inv[i], c, s); p.ropetab[t * 32 + 16 + i] = c; p.ropetab[t * 32 + 24 + i] = s;
.LBB0_45:
	v_readlane_b32 s0, v250, 10
	s_waitcnt lgkmcnt(0)
	s_barrier
	v_mbcnt_lo_u32_b32 v0, -1, 0
	v_mbcnt_hi_u32_b32 v0, -1, v0
	s_waitcnt vmcnt(0)
	v_add_u32_e32 v16, s0, v0
	v_add_u32_e32 v16, 0xffff0000, v16
	s_movk_i32 s0, 0x4000
	v_cmp_gt_u32_e32 vcc, s0, v16
	s_and_saveexec_b64 s[0:1], vcc
	s_cbranch_execz .LBB0_55
	v_and_b32_e32 v17, 7, v0
	v_readlane_b32 s6, v250, 2
	v_lshlrev_b32_e32 v0, 3, v17
	v_readlane_b32 s7, v250, 3
	v_ashrrev_i32_e32 v2, 9, v16
	s_mov_b32 s8, 0x54442d18
	v_cvt_f64_i32_e32 v[2:3], v2
	s_mov_b32 s9, 0x401921fb
	v_readlane_b32 s12, v253, 38
	global_load_dwordx2 v[6:7], v0, s[6:7] offset:424
	v_readlane_b32 s13, v253, 39
	s_mov_b32 s12, s8
	v_mov_b64_e32 v[4:5], 1.0
	s_mov_b32 s2, 4
	s_mov_b32 s10, 5
	s_mov_b32 s21, s13
	s_waitcnt vmcnt(0)
	v_mul_f64 v[8:9], v[6:7], v[2:3]
	v_div_scale_f64 v[10:11], s[4:5], s[8:9], s[8:9], v[8:9]
	v_rcp_f64_e32 v[12:13], v[10:11]
	v_div_scale_f64 v[14:15], vcc, v[8:9], s[8:9], v[8:9]
	v_lshl_add_u64 v[2:3], s[6:7], 0, v[0:1]
	v_fma_f64 v[18:19], -v[10:11], v[12:13], 1.0
	v_fmac_f64_e32 v[12:13], v[12:13], v[18:19]
	v_fma_f64 v[18:19], -v[10:11], v[12:13], 1.0
	v_fmac_f64_e32 v[12:13], v[12:13], v[18:19]
	v_mul_f64 v[18:19], v[14:15], v[12:13]
	v_fma_f64 v[10:11], -v[10:11], v[18:19], v[14:15]
	v_div_fmas_f64 v[10:11], v[10:11], v[12:13], v[18:19]
	v_div_fixup_f64 v[10:11], v[10:11], s[8:9], v[8:9]
	v_rndne_f64_e32 v[10:11], v[10:11]
	v_fmac_f64_e32 v[8:9], s[12:13], v[10:11]
	v_mul_f64 v[10:11], v[8:9], -v[8:9]
	v_mov_b64_e32 v[12:13], v[8:9]
	v_mov_b64_e32 v[14:15], 1.0

;   __device__ __forceinline__ void operator()(f32x4 (&acc)[2][2][4][2], int pm, int pn, int wr_, int wc_, int fr_, int fq_, bf16_t* shm, int tid) const {
;     ...
;       for (int n = 0; n < 2; ++n) {
;         asm volatile("" ::: "memory");
;         const int col = pn * 256 + bj * 128 + wc * 32 + n * 16 + fq * 4;
;         const f32x4 gg = *(const f32x4*)(ng + col), bb = *(const f32x4*)(nb + col);
;         f32x4 sh = {0.f, 0.f, 0.f, 0.f}, sc = {0.f, 0.f, 0.f, 0.f};
;         if (!outp) { sh = *(const f32x4*)(msh + bio + col); sc = *(const f32x4*)(msc + bio + col); }
; #pragma unroll
;         for (int ai = 0; ai < 2; ++ai)
; #pragma unroll
;           for (int m = 0; m < 4; ++m) {
;             const int rl = ai * 128 + wr * 64 + m * 16 + fr, row = pm * 256 + rl;
;             const f2_t st = rst[rl];
;             f32x4 y = (acc[ai][bj][m][n] - st[0]) * st[1] * gg + bb;
;             if (outp) { *(f32x4*)(outp + (long)row * DM + col) = y; }
.LBB0_238:
	v_lshl_add_u32 v142, v154, 3, 16
	v_add_u32_e32 v166, 0x22000, v142
	ds_read_b64 v[176:177], v166
	ds_read_b64 v[178:179], v166 offset:128
	ds_read_b64 v[180:181], v166 offset:256
	ds_read_b64 v[182:183], v166 offset:384
	ds_read_b64 v[184:185], v166 offset:1024
	ds_read_b64 v[186:187], v166 offset:1152
	ds_read_b64 v[188:189], v166 offset:1280
	ds_read_b64 v[190:191], v166 offset:1408
	s_waitcnt lgkmcnt(0)
	v_mov_b32_e32 v144, v176
	v_mov_b32_e32 v145, v177
	v_add_u32_e32 v148, s28, v154
	v_lshl_add_u64 v[142:143], v[0:1], 2, s[80:81]
	s_mov_b64 s[14:15], -1
	s_andn2_b64 vcc, exec, s[82:83]
	s_waitcnt lgkmcnt(0)
	v_sub_f32_e32 v5, v5, v144
	v_sub_f32_e32 v4, v4, v144
	v_sub_f32_e32 v3, v3, v144
	v_sub_f32_e32 v2, v2, v144
	v_pk_mul_f32 v[2:3], v[144:145], v[2:3] op_sel:[1,0]
	v_pk_mul_f32 v[4:5], v[144:145], v[4:5] op_sel:[1,0]
	v_cndmask_b32_e64 v144, 0, 1, s[82:83]
	s_waitcnt vmcnt(0)
	v_pk_fma_f32 v[4:5], v[136:137], v[4:5], v[140:141]
	v_pk_fma_f32 v[2:3], v[134:135], v[2:3], v[138:139]
	v_cmp_ne_u32_e64 s[8:9], 1, v144
	v_ashrrev_i32_e32 v149, 31, v148
	s_cbranch_vccnz .LBB0_240
	v_lshlrev_b64 v[144:145], 12, v[148:149]
	v_lshl_add_u64 v[144:145], v[142:143], 0, v[144:145]
	s_mov_b64 s[14:15], 0
	global_store_dwordx4 v[144:145], v[2:5], off

;   __device__ __forceinline__ void operator()(f32x4 (&acc)[2][2][4][2], int pm, int pn, int wr_, int wc_, int fr_, int fq_, bf16_t* shm, int tid) const {
;     ...
;         for (int ai = 0; ai < 2; ++ai)
; #pragma unroll
;           for (int m = 0; m < 4; ++m) {
;             const int rl = ai * 128 + wr * 64 + m * 16 + fr, row = pm * 256 + rl;
;             const f2_t st = rst[rl];
;             f32x4 y = (acc[ai][bj][m][n] - st[0]) * st[1] * gg + bb;
;             if (outp) { *(f32x4*)(outp + (long)row * DM + col) = y; }
.LBB0_242:
	v_or_b32_e32 v4, 16, v154
	v_lshl_add_u32 v0, v4, 3, 16
	v_add_u32_e32 v0, 0x22000, v0
	v_mov_b32_e32 v2, v178
	v_mov_b32_e32 v3, v179
	v_add_u32_e32 v150, s28, v4
	s_mov_b64 s[14:15], -1
	s_and_b64 vcc, exec, s[8:9]
	v_ashrrev_i32_e32 v151, 31, v150
	s_waitcnt lgkmcnt(0)
	v_sub_f32_e32 v5, v9, v2
	v_sub_f32_e32 v4, v8, v2
	v_sub_f32_e32 v7, v7, v2
	v_sub_f32_e32 v6, v6, v2
	v_pk_mul_f32 v[6:7], v[2:3], v[6:7] op_sel:[1,0]
	v_pk_mul_f32 v[2:3], v[2:3], v[4:5] op_sel:[1,0]
	s_nop 0
	v_pk_fma_f32 v[4:5], v[136:137], v[2:3], v[140:141]
	v_pk_fma_f32 v[2:3], v[134:135], v[6:7], v[138:139]
	s_cbranch_vccnz .LBB0_244
	v_lshlrev_b64 v[6:7], 12, v[150:151]
	v_lshl_add_u64 v[6:7], v[142:143], 0, v[6:7]
	s_mov_b64 s[14:15], 0
	global_store_dwordx4 v[6:7], v[2:5], off

;   __device__ __forceinline__ void operator()(f32x4 (&acc)[2][2][4][2], int pm, int pn, int wr_, int wc_, int fr_, int fq_, bf16_t* shm, int tid) const {
;     ...
;         for (int ai = 0; ai < 2; ++ai)
; #pragma unroll
;           for (int m = 0; m < 4; ++m) {
;             const int rl = ai * 128 + wr * 64 + m * 16 + fr, row = pm * 256 + rl;
;             const f2_t st = rst[rl];
;             f32x4 y = (acc[ai][bj][m][n] - st[0]) * st[1] * gg + bb;
;             if (outp) { *(f32x4*)(outp + (long)row * DM + col) = y; }
.LBB0_246:
	v_or_b32_e32 v4, 32, v154
	v_lshl_add_u32 v2, v4, 3, 16
	v_add_u32_e32 v167, 0x22000, v2
	v_mov_b32_e32 v2, v180
	v_mov_b32_e32 v3, v181
	v_add_u32_e32 v152, s28, v4
	s_mov_b64 s[14:15], -1
	s_and_b64 vcc, exec, s[8:9]
	v_ashrrev_i32_e32 v153, 31, v152
	s_waitcnt lgkmcnt(0)
	v_sub_f32_e32 v5, v13, v2
	v_sub_f32_e32 v4, v12, v2
	v_sub_f32_e32 v7, v11, v2
	v_sub_f32_e32 v6, v10, v2
	v_pk_mul_f32 v[6:7], v[2:3], v[6:7] op_sel:[1,0]
	v_pk_mul_f32 v[2:3], v[2:3], v[4:5] op_sel:[1,0]
	s_nop 0
	v_pk_fma_f32 v[4:5], v[136:137], v[2:3], v[140:141]
	v_pk_fma_f32 v[2:3], v[134:135], v[6:7], v[138:139]
	s_cbranch_vccnz .LBB0_248
	v_lshlrev_b64 v[6:7], 12, v[152:153]
	v_lshl_add_u64 v[6:7], v[142:143], 0, v[6:7]
	s_mov_b64 s[14:15], 0
	global_store_dwordx4 v[6:7], v[2:5], off

;   __device__ __forceinline__ void operator()(f32x4 (&acc)[2][2][4][2], int pm, int pn, int wr_, int wc_, int fr_, int fq_, bf16_t* shm, int tid) const {
;     ...
;         for (int ai = 0; ai < 2; ++ai)
; #pragma unroll
;           for (int m = 0; m < 4; ++m) {
;             const int rl = ai * 128 + wr * 64 + m * 16 + fr, row = pm * 256 + rl;
;             const f2_t st = rst[rl];
;             f32x4 y = (acc[ai][bj][m][n] - st[0]) * st[1] * gg + bb;
;             if (outp) { *(f32x4*)(outp + (long)row * DM + col) = y; }
.LBB0_250:
	v_or_b32_e32 v4, 48, v154
	v_lshl_add_u32 v2, v4, 3, 16
	v_add_u32_e32 v168, 0x22000, v2
	v_mov_b32_e32 v2, v182
	v_mov_b32_e32 v3, v183
	v_add_u32_e32 v154, s28, v4
	s_mov_b64 s[14:15], -1
	s_and_b64 vcc, exec, s[8:9]
	v_ashrrev_i32_e32 v155, 31, v154
	s_waitcnt lgkmcnt(0)
	v_sub_f32_e32 v5, v17, v2
	v_sub_f32_e32 v4, v16, v2
	v_sub_f32_e32 v7, v15, v2
	v_sub_f32_e32 v6, v14, v2
	v_pk_mul_f32 v[6:7], v[2:3], v[6:7] op_sel:[1,0]
	v_pk_mul_f32 v[2:3], v[2:3], v[4:5] op_sel:[1,0]
	s_nop 0
	v_pk_fma_f32 v[4:5], v[136:137], v[2:3], v[140:141]
	v_pk_fma_f32 v[2:3], v[134:135], v[6:7], v[138:139]
	s_cbranch_vccnz .LBB0_252
	v_lshlrev_b64 v[6:7], 12, v[154:155]
	v_lshl_add_u64 v[6:7], v[142:143], 0, v[6:7]
	s_mov_b64 s[14:15], 0
	global_store_dwordx4 v[6:7], v[2:5], off

;   __device__ __forceinline__ void operator()(f32x4 (&acc)[2][2][4][2], int pm, int pn, int wr_, int wc_, int fr_, int fq_, bf16_t* shm, int tid) const {
;     ...
;         for (int ai = 0; ai < 2; ++ai)
; #pragma unroll
;           for (int m = 0; m < 4; ++m) {
;             const int rl = ai * 128 + wr * 64 + m * 16 + fr, row = pm * 256 + rl;
;             const f2_t st = rst[rl];
;             f32x4 y = (acc[ai][bj][m][n] - st[0]) * st[1] * gg + bb;
;             if (outp) { *(f32x4*)(outp + (long)row * DM + col) = y; }
.LBB0_254:
	v_mov_b32_e32 v2, v184
	v_mov_b32_e32 v3, v185
	v_add_u32_e32 v156, 0x80, v148
	s_mov_b64 s[14:15], -1
	s_and_b64 vcc, exec, s[8:9]
	v_ashrrev_i32_e32 v157, 31, v156
	s_waitcnt lgkmcnt(0)
	v_sub_f32_e32 v5, v21, v2
	v_sub_f32_e32 v4, v20, v2
	v_sub_f32_e32 v7, v19, v2
	v_sub_f32_e32 v6, v18, v2
	v_pk_mul_f32 v[6:7], v[2:3], v[6:7] op_sel:[1,0]
	v_pk_mul_f32 v[2:3], v[2:3], v[4:5] op_sel:[1,0]
	s_nop 0
	v_pk_fma_f32 v[4:5], v[136:137], v[2:3], v[140:141]
	v_pk_fma_f32 v[2:3], v[134:135], v[6:7], v[138:139]
	s_cbranch_vccnz .LBB0_256
	v_lshlrev_b64 v[6:7], 12, v[156:157]
	v_lshl_add_u64 v[6:7], v[142:143], 0, v[6:7]
	s_mov_b64 s[14:15], 0
	global_store_dwordx4 v[6:7], v[2:5], off

;   __device__ __forceinline__ void operator()(f32x4 (&acc)[2][2][4][2], int pm, int pn, int wr_, int wc_, int fr_, int fq_, bf16_t* shm, int tid) const {
;     ...
;         for (int ai = 0; ai < 2; ++ai)
; #pragma unroll
;           for (int m = 0; m < 4; ++m) {
;             const int rl = ai * 128 + wr * 64 + m * 16 + fr, row = pm * 256 + rl;
;             const f2_t st = rst[rl];
;             f32x4 y = (acc[ai][bj][m][n] - st[0]) * st[1] * gg + bb;
;             if (outp) { *(f32x4*)(outp + (long)row * DM + col) = y; }
.LBB0_258:
	v_mov_b32_e32 v2, v186
	v_mov_b32_e32 v3, v187
	v_add_u32_e32 v18, 0x90, v148
	s_mov_b64 s[14:15], -1
	s_and_b64 vcc, exec, s[8:9]
	v_ashrrev_i32_e32 v19, 31, v18
	s_waitcnt lgkmcnt(0)
	v_sub_f32_e32 v5, v25, v2
	v_sub_f32_e32 v4, v24, v2
	v_sub_f32_e32 v7, v23, v2
	v_sub_f32_e32 v6, v22, v2
	v_pk_mul_f32 v[6:7], v[2:3], v[6:7] op_sel:[1,0]
	v_pk_mul_f32 v[2:3], v[2:3], v[4:5] op_sel:[1,0]
	s_nop 0
	v_pk_fma_f32 v[4:5], v[136:137], v[2:3], v[140:141]
	v_pk_fma_f32 v[2:3], v[134:135], v[6:7], v[138:139]
	s_cbranch_vccnz .LBB0_260
	v_lshlrev_b64 v[6:7], 12, v[18:19]
	v_lshl_add_u64 v[6:7], v[142:143], 0, v[6:7]
	s_mov_b64 s[14:15], 0
	global_store_dwordx4 v[6:7], v[2:5], off

;   __device__ __forceinline__ void operator()(f32x4 (&acc)[2][2][4][2], int pm, int pn, int wr_, int wc_, int fr_, int fq_, bf16_t* shm, int tid) const {
;     ...
;         for (int ai = 0; ai < 2; ++ai)
; #pragma unroll
;           for (int m = 0; m < 4; ++m) {
;             const int rl = ai * 128 + wr * 64 + m * 16 + fr, row = pm * 256 + rl;
;             const f2_t st = rst[rl];
;             f32x4 y = (acc[ai][bj][m][n] - st[0]) * st[1] * gg + bb;
;             if (outp) { *(f32x4*)(outp + (long)row * DM + col) = y; }
.LBB0_262:
	v_mov_b32_e32 v2, v188
	v_mov_b32_e32 v3, v189
	v_add_u32_e32 v20, 0xa0, v148
	s_mov_b64 s[14:15], -1
	s_and_b64 vcc, exec, s[8:9]
	v_ashrrev_i32_e32 v21, 31, v20
	s_waitcnt lgkmcnt(0)
	v_sub_f32_e32 v5, v29, v2
	v_sub_f32_e32 v4, v28, v2
	v_sub_f32_e32 v7, v27, v2
	v_sub_f32_e32 v6, v26, v2
	v_pk_mul_f32 v[6:7], v[2:3], v[6:7] op_sel:[1,0]
	v_pk_mul_f32 v[2:3], v[2:3], v[4:5] op_sel:[1,0]
	s_nop 0
	v_pk_fma_f32 v[4:5], v[136:137], v[2:3], v[140:141]
	v_pk_fma_f32 v[2:3], v[134:135], v[6:7], v[138:139]
	s_cbranch_vccnz .LBB0_264
	v_lshlrev_b64 v[6:7], 12, v[20:21]
	v_lshl_add_u64 v[6:7], v[142:143], 0, v[6:7]
	s_mov_b64 s[14:15], 0
	global_store_dwordx4 v[6:7], v[2:5], off

;   __device__ __forceinline__ void operator()(f32x4 (&acc)[2][2][4][2], int pm, int pn, int wr_, int wc_, int fr_, int fq_, bf16_t* shm, int tid) const {
;     ...
;         for (int ai = 0; ai < 2; ++ai)
; #pragma unroll
;           for (int m = 0; m < 4; ++m) {
;             const int rl = ai * 128 + wr * 64 + m * 16 + fr, row = pm * 256 + rl;
;             const f2_t st = rst[rl];
;             f32x4 y = (acc[ai][bj][m][n] - st[0]) * st[1] * gg + bb;
;             if (outp) { *(f32x4*)(outp + (long)row * DM + col) = y; }
.LBB0_266:
	v_mov_b32_e32 v2, v190
	v_mov_b32_e32 v3, v191
	v_add_u32_e32 v22, 0xb0, v148
	s_mov_b64 s[14:15], -1
	s_and_b64 vcc, exec, s[8:9]
	v_ashrrev_i32_e32 v23, 31, v22
	s_waitcnt lgkmcnt(0)
	v_sub_f32_e32 v5, v37, v2
	v_sub_f32_e32 v4, v36, v2
	v_sub_f32_e32 v7, v35, v2
	v_sub_f32_e32 v6, v34, v2
	v_pk_mul_f32 v[6:7], v[2:3], v[6:7] op_sel:[1,0]
	v_pk_mul_f32 v[2:3], v[2:3], v[4:5] op_sel:[1,0]
	s_nop 0
	v_pk_fma_f32 v[4:5], v[136:137], v[2:3], v[140:141]
	v_pk_fma_f32 v[2:3], v[134:135], v[6:7], v[138:139]
	s_cbranch_vccnz .LBB0_268
	v_lshlrev_b64 v[6:7], 12, v[22:23]
	v_lshl_add_u64 v[6:7], v[142:143], 0, v[6:7]
	s_mov_b64 s[14:15], 0
	global_store_dwordx4 v[6:7], v[2:5], off

;   __device__ __forceinline__ void operator()(f32x4 (&acc)[2][2][4][2], int pm, int pn, int wr_, int wc_, int fr_, int fq_, bf16_t* shm, int tid) const {
;     ...
;       for (int n = 0; n < 2; ++n) {
;         asm volatile("" ::: "memory");
;         const int col = pn * 256 + bj * 128 + wc * 32 + n * 16 + fq * 4;
;         const f32x4 gg = *(const f32x4*)(ng + col), bb = *(const f32x4*)(nb + col);
;         f32x4 sh = {0.f, 0.f, 0.f, 0.f}, sc = {0.f, 0.f, 0.f, 0.f};
;         if (!outp) { sh = *(const f32x4*)(msh + bio + col); sc = *(const f32x4*)(msc + bio + col); }
; #pragma unroll
;         for (int ai = 0; ai < 2; ++ai)
; #pragma unroll
;           for (int m = 0; m < 4; ++m) {
;             const int rl = ai * 128 + wr * 64 + m * 16 + fr, row = pm * 256 + rl;
;             const f2_t st = rst[rl];
;             f32x4 y = (acc[ai][bj][m][n] - st[0]) * st[1] * gg + bb;
;             if (outp) { *(f32x4*)(outp + (long)row * DM + col) = y; }
.LBB0_273:
	v_mov_b32_e32 v14, v176
	v_mov_b32_e32 v15, v177
	s_and_b64 vcc, exec, s[8:9]
	s_mov_b64 s[14:15], -1
	s_waitcnt lgkmcnt(0)
	v_sub_f32_e32 v17, v33, v14
	v_sub_f32_e32 v16, v32, v14
	v_sub_f32_e32 v29, v31, v14
	v_sub_f32_e32 v28, v30, v14
	v_pk_mul_f32 v[28:29], v[14:15], v[28:29] op_sel:[1,0]
	v_pk_mul_f32 v[14:15], v[14:15], v[16:17] op_sel:[1,0]
	s_waitcnt vmcnt(0)
	v_pk_fma_f32 v[16:17], v[8:9], v[14:15], v[12:13]
	v_pk_fma_f32 v[14:15], v[6:7], v[28:29], v[10:11]
	s_cbranch_vccnz .LBB0_275
	v_lshlrev_b64 v[28:29], 12, v[148:149]
	v_lshl_add_u64 v[28:29], v[142:143], 0, v[28:29]
	s_mov_b64 s[14:15], 0
	global_store_dwordx4 v[28:29], v[14:17], off offset:64

;   __device__ __forceinline__ void operator()(f32x4 (&acc)[2][2][4][2], int pm, int pn, int wr_, int wc_, int fr_, int fq_, bf16_t* shm, int tid) const {
;     ...
;         for (int ai = 0; ai < 2; ++ai)
; #pragma unroll
;           for (int m = 0; m < 4; ++m) {
;             const int rl = ai * 128 + wr * 64 + m * 16 + fr, row = pm * 256 + rl;
;             const f2_t st = rst[rl];
;             f32x4 y = (acc[ai][bj][m][n] - st[0]) * st[1] * gg + bb;
;             if (outp) { *(f32x4*)(outp + (long)row * DM + col) = y; }
.LBB0_277:
	v_mov_b32_e32 v14, v178
	v_mov_b32_e32 v15, v179
	s_and_b64 vcc, exec, s[8:9]
	s_mov_b64 s[14:15], -1
	s_waitcnt lgkmcnt(0)
	v_sub_f32_e32 v17, v41, v14
	v_sub_f32_e32 v16, v40, v14
	v_sub_f32_e32 v29, v39, v14
	v_sub_f32_e32 v28, v38, v14
	v_pk_mul_f32 v[28:29], v[14:15], v[28:29] op_sel:[1,0]
	v_pk_mul_f32 v[14:15], v[14:15], v[16:17] op_sel:[1,0]
	s_nop 0
	v_pk_fma_f32 v[16:17], v[8:9], v[14:15], v[12:13]
	v_pk_fma_f32 v[14:15], v[6:7], v[28:29], v[10:11]
	s_cbranch_vccnz .LBB0_279
	v_lshlrev_b64 v[28:29], 12, v[150:151]
	v_lshl_add_u64 v[28:29], v[142:143], 0, v[28:29]
	s_mov_b64 s[14:15], 0
	global_store_dwordx4 v[28:29], v[14:17], off offset:64

;   __device__ __forceinline__ void operator()(f32x4 (&acc)[2][2][4][2], int pm, int pn, int wr_, int wc_, int fr_, int fq_, bf16_t* shm, int tid) const {
;     ...
;         for (int ai = 0; ai < 2; ++ai)
; #pragma unroll
;           for (int m = 0; m < 4; ++m) {
;             const int rl = ai * 128 + wr * 64 + m * 16 + fr, row = pm * 256 + rl;
;             const f2_t st = rst[rl];
;             f32x4 y = (acc[ai][bj][m][n] - st[0]) * st[1] * gg + bb;
;             if (outp) { *(f32x4*)(outp + (long)row * DM + col) = y; }
.LBB0_281:
	v_mov_b32_e32 v14, v180
	v_mov_b32_e32 v15, v181
	s_and_b64 vcc, exec, s[8:9]
	s_mov_b64 s[14:15], -1
	s_waitcnt lgkmcnt(0)
	v_sub_f32_e32 v17, v45, v14
	v_sub_f32_e32 v16, v44, v14
	v_sub_f32_e32 v29, v43, v14
	v_sub_f32_e32 v28, v42, v14
	v_pk_mul_f32 v[28:29], v[14:15], v[28:29] op_sel:[1,0]
	v_pk_mul_f32 v[14:15], v[14:15], v[16:17] op_sel:[1,0]
	s_nop 0
	v_pk_fma_f32 v[16:17], v[8:9], v[14:15], v[12:13]
	v_pk_fma_f32 v[14:15], v[6:7], v[28:29], v[10:11]
	s_cbranch_vccnz .LBB0_283
	v_lshlrev_b64 v[28:29], 12, v[152:153]
	v_lshl_add_u64 v[28:29], v[142:143], 0, v[28:29]
	s_mov_b64 s[14:15], 0
	global_store_dwordx4 v[28:29], v[14:17], off offset:64

;   __device__ __forceinline__ void operator()(f32x4 (&acc)[2][2][4][2], int pm, int pn, int wr_, int wc_, int fr_, int fq_, bf16_t* shm, int tid) const {
;     ...
;         for (int ai = 0; ai < 2; ++ai)
; #pragma unroll
;           for (int m = 0; m < 4; ++m) {
;             const int rl = ai * 128 + wr * 64 + m * 16 + fr, row = pm * 256 + rl;
;             const f2_t st = rst[rl];
;             f32x4 y = (acc[ai][bj][m][n] - st[0]) * st[1] * gg + bb;
;             if (outp) { *(f32x4*)(outp + (long)row * DM + col) = y; }
.LBB0_285:
	v_mov_b32_e32 v14, v182
	v_mov_b32_e32 v15, v183
	s_and_b64 vcc, exec, s[8:9]
	s_mov_b64 s[14:15], -1
	s_waitcnt lgkmcnt(0)
	v_sub_f32_e32 v17, v49, v14
	v_sub_f32_e32 v16, v48, v14
	v_sub_f32_e32 v29, v47, v14
	v_sub_f32_e32 v28, v46, v14
	v_pk_mul_f32 v[28:29], v[14:15], v[28:29] op_sel:[1,0]
	v_pk_mul_f32 v[14:15], v[14:15], v[16:17] op_sel:[1,0]
	s_nop 0
	v_pk_fma_f32 v[16:17], v[8:9], v[14:15], v[12:13]
	v_pk_fma_f32 v[14:15], v[6:7], v[28:29], v[10:11]
	s_cbranch_vccnz .LBB0_287
	v_lshlrev_b64 v[28:29], 12, v[154:155]
	v_lshl_add_u64 v[28:29], v[142:143], 0, v[28:29]
	s_mov_b64 s[14:15], 0
	global_store_dwordx4 v[28:29], v[14:17], off offset:64

;   __device__ __forceinline__ void operator()(f32x4 (&acc)[2][2][4][2], int pm, int pn, int wr_, int wc_, int fr_, int fq_, bf16_t* shm, int tid) const {
;     ...
;         for (int ai = 0; ai < 2; ++ai)
; #pragma unroll
;           for (int m = 0; m < 4; ++m) {
;             const int rl = ai * 128 + wr * 64 + m * 16 + fr, row = pm * 256 + rl;
;             const f2_t st = rst[rl];
;             f32x4 y = (acc[ai][bj][m][n] - st[0]) * st[1] * gg + bb;
;             if (outp) { *(f32x4*)(outp + (long)row * DM + col) = y; }
.LBB0_289:
	v_mov_b32_e32 v14, v184
	v_mov_b32_e32 v15, v185
	s_and_b64 vcc, exec, s[8:9]
	s_mov_b64 s[14:15], -1
	s_waitcnt lgkmcnt(0)
	v_sub_f32_e32 v17, v53, v14
	v_sub_f32_e32 v16, v52, v14
	v_sub_f32_e32 v29, v51, v14
	v_sub_f32_e32 v28, v50, v14
	v_pk_mul_f32 v[28:29], v[14:15], v[28:29] op_sel:[1,0]
	v_pk_mul_f32 v[14:15], v[14:15], v[16:17] op_sel:[1,0]
	s_nop 0
	v_pk_fma_f32 v[16:17], v[8:9], v[14:15], v[12:13]
	v_pk_fma_f32 v[14:15], v[6:7], v[28:29], v[10:11]
	s_cbranch_vccnz .LBB0_291
	v_lshlrev_b64 v[28:29], 12, v[156:157]
	v_lshl_add_u64 v[28:29], v[142:143], 0, v[28:29]
	s_mov_b64 s[14:15], 0
	global_store_dwordx4 v[28:29], v[14:17], off offset:64

;   __device__ __forceinline__ void operator()(f32x4 (&acc)[2][2][4][2], int pm, int pn, int wr_, int wc_, int fr_, int fq_, bf16_t* shm, int tid) const {
;     ...
;         for (int ai = 0; ai < 2; ++ai)
; #pragma unroll
;           for (int m = 0; m < 4; ++m) {
;             const int rl = ai * 128 + wr * 64 + m * 16 + fr, row = pm * 256 + rl;
;             const f2_t st = rst[rl];
;             f32x4 y = (acc[ai][bj][m][n] - st[0]) * st[1] * gg + bb;
;             if (outp) { *(f32x4*)(outp + (long)row * DM + col) = y; }
.LBB0_293:
	v_mov_b32_e32 v14, v186
	v_mov_b32_e32 v15, v187
	s_and_b64 vcc, exec, s[8:9]
	s_mov_b64 s[14:15], -1
	s_waitcnt lgkmcnt(0)
	v_sub_f32_e32 v17, v57, v14
	v_sub_f32_e32 v16, v56, v14
	v_sub_f32_e32 v29, v55, v14
	v_sub_f32_e32 v28, v54, v14
	v_pk_mul_f32 v[28:29], v[14:15], v[28:29] op_sel:[1,0]
	v_pk_mul_f32 v[14:15], v[14:15], v[16:17] op_sel:[1,0]
	s_nop 0
	v_pk_fma_f32 v[16:17], v[8:9], v[14:15], v[12:13]
	v_pk_fma_f32 v[14:15], v[6:7], v[28:29], v[10:11]
	s_cbranch_vccnz .LBB0_295
	v_lshlrev_b64 v[28:29], 12, v[18:19]
	v_lshl_add_u64 v[28:29], v[142:143], 0, v[28:29]
	s_mov_b64 s[14:15], 0
	global_store_dwordx4 v[28:29], v[14:17], off offset:64

;   __device__ __forceinline__ void operator()(f32x4 (&acc)[2][2][4][2], int pm, int pn, int wr_, int wc_, int fr_, int fq_, bf16_t* shm, int tid) const {
;     ...
;         for (int ai = 0; ai < 2; ++ai)
; #pragma unroll
;           for (int m = 0; m < 4; ++m) {
;             const int rl = ai * 128 + wr * 64 + m * 16 + fr, row = pm * 256 + rl;
;             const f2_t st = rst[rl];
;             f32x4 y = (acc[ai][bj][m][n] - st[0]) * st[1] * gg + bb;
;             if (outp) { *(f32x4*)(outp + (long)row * DM + col) = y; }
.LBB0_297:
	v_mov_b32_e32 v14, v188
	v_mov_b32_e32 v15, v189
	s_and_b64 vcc, exec, s[8:9]
	s_mov_b64 s[14:15], -1
	s_waitcnt lgkmcnt(0)
	v_sub_f32_e32 v17, v61, v14
	v_sub_f32_e32 v16, v60, v14
	v_sub_f32_e32 v29, v59, v14
	v_sub_f32_e32 v28, v58, v14
	v_pk_mul_f32 v[28:29], v[14:15], v[28:29] op_sel:[1,0]
	v_pk_mul_f32 v[14:15], v[14:15], v[16:17] op_sel:[1,0]
	s_nop 0
	v_pk_fma_f32 v[16:17], v[8:9], v[14:15], v[12:13]
	v_pk_fma_f32 v[14:15], v[6:7], v[28:29], v[10:11]
	s_cbranch_vccnz .LBB0_299
	v_lshlrev_b64 v[28:29], 12, v[20:21]
	v_lshl_add_u64 v[28:29], v[142:143], 0, v[28:29]
	s_mov_b64 s[14:15], 0
	global_store_dwordx4 v[28:29], v[14:17], off offset:64

;   __device__ __forceinline__ void operator()(f32x4 (&acc)[2][2][4][2], int pm, int pn, int wr_, int wc_, int fr_, int fq_, bf16_t* shm, int tid) const {
;     ...
;         for (int ai = 0; ai < 2; ++ai)
; #pragma unroll
;           for (int m = 0; m < 4; ++m) {
;             const int rl = ai * 128 + wr * 64 + m * 16 + fr, row = pm * 256 + rl;
;             const f2_t st = rst[rl];
;             f32x4 y = (acc[ai][bj][m][n] - st[0]) * st[1] * gg + bb;
;             if (outp) { *(f32x4*)(outp + (long)row * DM + col) = y; }
.LBB0_301:
	v_mov_b32_e32 v14, v190
	v_mov_b32_e32 v15, v191
	s_and_b64 vcc, exec, s[8:9]
	s_mov_b64 s[14:15], -1
	s_waitcnt lgkmcnt(0)
	v_sub_f32_e32 v17, v69, v14
	v_sub_f32_e32 v16, v68, v14
	v_sub_f32_e32 v29, v67, v14
	v_sub_f32_e32 v28, v66, v14
	v_pk_mul_f32 v[28:29], v[14:15], v[28:29] op_sel:[1,0]
	v_pk_mul_f32 v[14:15], v[14:15], v[16:17] op_sel:[1,0]
	v_pk_fma_f32 v[6:7], v[6:7], v[28:29], v[10:11]
	v_pk_fma_f32 v[8:9], v[8:9], v[14:15], v[12:13]
	s_cbranch_vccnz .LBB0_303
	v_lshlrev_b64 v[10:11], 12, v[22:23]
	v_lshl_add_u64 v[10:11], v[142:143], 0, v[10:11]
	s_mov_b64 s[14:15], 0
	global_store_dwordx4 v[10:11], v[6:9], off offset:64

;   __device__ __forceinline__ void operator()(f32x4 (&acc)[2][2][4][2], int pm, int pn, int wr_, int wc_, int fr_, int fq_, bf16_t* shm, int tid) const {
;     ...
;       for (int n = 0; n < 2; ++n) {
;         asm volatile("" ::: "memory");
;         const int col = pn * 256 + bj * 128 + wc * 32 + n * 16 + fq * 4;
;         const f32x4 gg = *(const f32x4*)(ng + col), bb = *(const f32x4*)(nb + col);
;         f32x4 sh = {0.f, 0.f, 0.f, 0.f}, sc = {0.f, 0.f, 0.f, 0.f};
;         if (!outp) { sh = *(const f32x4*)(msh + bio + col); sc = *(const f32x4*)(msc + bio + col); }
; #pragma unroll
;         for (int ai = 0; ai < 2; ++ai)
; #pragma unroll
;           for (int m = 0; m < 4; ++m) {
;             const int rl = ai * 128 + wr * 64 + m * 16 + fr, row = pm * 256 + rl;
;             const f2_t st = rst[rl];
;             f32x4 y = (acc[ai][bj][m][n] - st[0]) * st[1] * gg + bb;
;             if (outp) { *(f32x4*)(outp + (long)row * DM + col) = y; }
.LBB0_308:
	v_mov_b32_e32 v14, v176
	v_mov_b32_e32 v15, v177
	s_and_b64 vcc, exec, s[8:9]
	s_mov_b64 s[14:15], -1
	s_waitcnt lgkmcnt(0)
	v_sub_f32_e32 v17, v65, v14
	v_sub_f32_e32 v16, v64, v14
	v_sub_f32_e32 v29, v63, v14
	v_sub_f32_e32 v28, v62, v14
	v_pk_mul_f32 v[28:29], v[14:15], v[28:29] op_sel:[1,0]
	v_pk_mul_f32 v[14:15], v[14:15], v[16:17] op_sel:[1,0]
	s_waitcnt vmcnt(0)
	v_pk_fma_f32 v[16:17], v[8:9], v[14:15], v[12:13]
	v_pk_fma_f32 v[14:15], v[6:7], v[28:29], v[10:11]
	s_cbranch_vccnz .LBB0_310
	v_lshlrev_b64 v[28:29], 12, v[148:149]
	v_lshl_add_u64 v[28:29], v[142:143], 0, v[28:29]
	s_mov_b64 s[14:15], 0
	global_store_dwordx4 v[28:29], v[14:17], off offset:512

;   __device__ __forceinline__ void operator()(f32x4 (&acc)[2][2][4][2], int pm, int pn, int wr_, int wc_, int fr_, int fq_, bf16_t* shm, int tid) const {
;     ...
;         for (int ai = 0; ai < 2; ++ai)
; #pragma unroll
;           for (int m = 0; m < 4; ++m) {
;             const int rl = ai * 128 + wr * 64 + m * 16 + fr, row = pm * 256 + rl;
;             const f2_t st = rst[rl];
;             f32x4 y = (acc[ai][bj][m][n] - st[0]) * st[1] * gg + bb;
;             if (outp) { *(f32x4*)(outp + (long)row * DM + col) = y; }
.LBB0_312:
	v_mov_b32_e32 v14, v178
	v_mov_b32_e32 v15, v179
	s_and_b64 vcc, exec, s[8:9]
	s_mov_b64 s[14:15], -1
	s_waitcnt lgkmcnt(0)
	v_sub_f32_e32 v17, v73, v14
	v_sub_f32_e32 v16, v72, v14
	v_sub_f32_e32 v29, v71, v14
	v_sub_f32_e32 v28, v70, v14
	v_pk_mul_f32 v[28:29], v[14:15], v[28:29] op_sel:[1,0]
	v_pk_mul_f32 v[14:15], v[14:15], v[16:17] op_sel:[1,0]
	s_nop 0
	v_pk_fma_f32 v[16:17], v[8:9], v[14:15], v[12:13]
	v_pk_fma_f32 v[14:15], v[6:7], v[28:29], v[10:11]
	s_cbranch_vccnz .LBB0_314
	v_lshlrev_b64 v[28:29], 12, v[150:151]
	v_lshl_add_u64 v[28:29], v[142:143], 0, v[28:29]
	s_mov_b64 s[14:15], 0
	global_store_dwordx4 v[28:29], v[14:17], off offset:512

;   __device__ __forceinline__ void operator()(f32x4 (&acc)[2][2][4][2], int pm, int pn, int wr_, int wc_, int fr_, int fq_, bf16_t* shm, int tid) const {
;     ...
;         for (int ai = 0; ai < 2; ++ai)
; #pragma unroll
;           for (int m = 0; m < 4; ++m) {
;             const int rl = ai * 128 + wr * 64 + m * 16 + fr, row = pm * 256 + rl;
;             const f2_t st = rst[rl];
;             f32x4 y = (acc[ai][bj][m][n] - st[0]) * st[1] * gg + bb;
;             if (outp) { *(f32x4*)(outp + (long)row * DM + col) = y; }
.LBB0_316:
	v_mov_b32_e32 v14, v180
	v_mov_b32_e32 v15, v181
	s_and_b64 vcc, exec, s[8:9]
	s_mov_b64 s[14:15], -1
	s_waitcnt lgkmcnt(0)
	v_sub_f32_e32 v17, v77, v14
	v_sub_f32_e32 v16, v76, v14
	v_sub_f32_e32 v29, v75, v14
	v_sub_f32_e32 v28, v74, v14
	v_pk_mul_f32 v[28:29], v[14:15], v[28:29] op_sel:[1,0]
	v_pk_mul_f32 v[14:15], v[14:15], v[16:17] op_sel:[1,0]
	s_nop 0
	v_pk_fma_f32 v[16:17], v[8:9], v[14:15], v[12:13]
	v_pk_fma_f32 v[14:15], v[6:7], v[28:29], v[10:11]
	s_cbranch_vccnz .LBB0_318
	v_lshlrev_b64 v[28:29], 12, v[152:153]
	v_lshl_add_u64 v[28:29], v[142:143], 0, v[28:29]
	s_mov_b64 s[14:15], 0
	global_store_dwordx4 v[28:29], v[14:17], off offset:512

;   __device__ __forceinline__ void operator()(f32x4 (&acc)[2][2][4][2], int pm, int pn, int wr_, int wc_, int fr_, int fq_, bf16_t* shm, int tid) const {
;     ...
;             const int rl = ai * 128 + wr * 64 + m * 16 + fr, row = pm * 256 + rl;
;             const f2_t st = rst[rl];
;             f32x4 y = (acc[ai][bj][m][n] - st[0]) * st[1] * gg + bb;
;             if (outp) { *(f32x4*)(outp + (long)row * DM + col) = y; }
.LBB0_320:
	v_mov_b32_e32 v14, v182
	v_mov_b32_e32 v15, v183
	s_and_b64 vcc, exec, s[8:9]
	s_mov_b64 s[14:15], -1
	s_waitcnt lgkmcnt(0)
	v_sub_f32_e32 v17, v81, v14
	v_sub_f32_e32 v16, v80, v14
	v_sub_f32_e32 v29, v79, v14
	v_sub_f32_e32 v28, v78, v14
	v_pk_mul_f32 v[28:29], v[14:15], v[28:29] op_sel:[1,0]
	v_pk_mul_f32 v[14:15], v[14:15], v[16:17] op_sel:[1,0]
	s_nop 0
	v_pk_fma_f32 v[16:17], v[8:9], v[14:15], v[12:13]
	v_pk_fma_f32 v[14:15], v[6:7], v[28:29], v[10:11]
	s_cbranch_vccnz .LBB0_322
	v_lshlrev_b64 v[28:29], 12, v[154:155]
	v_lshl_add_u64 v[28:29], v[142:143], 0, v[28:29]
	s_mov_b64 s[14:15], 0
	global_store_dwordx4 v[28:29], v[14:17], off offset:512

;   __device__ __forceinline__ void operator()(f32x4 (&acc)[2][2][4][2], int pm, int pn, int wr_, int wc_, int fr_, int fq_, bf16_t* shm, int tid) const {
;     ...
;             const int rl = ai * 128 + wr * 64 + m * 16 + fr, row = pm * 256 + rl;
;             const f2_t st = rst[rl];
;             f32x4 y = (acc[ai][bj][m][n] - st[0]) * st[1] * gg + bb;
;             if (outp) { *(f32x4*)(outp + (long)row * DM + col) = y; }
.LBB0_324:
	v_mov_b32_e32 v14, v184
	v_mov_b32_e32 v15, v185
	s_and_b64 vcc, exec, s[8:9]
	s_mov_b64 s[14:15], -1
	s_waitcnt lgkmcnt(0)
	v_sub_f32_e32 v17, v85, v14
	v_sub_f32_e32 v16, v84, v14
	v_sub_f32_e32 v29, v83, v14
	v_sub_f32_e32 v28, v82, v14
	v_pk_mul_f32 v[28:29], v[14:15], v[28:29] op_sel:[1,0]
	v_pk_mul_f32 v[14:15], v[14:15], v[16:17] op_sel:[1,0]
	s_nop 0
	v_pk_fma_f32 v[16:17], v[8:9], v[14:15], v[12:13]
	v_pk_fma_f32 v[14:15], v[6:7], v[28:29], v[10:11]
	s_cbranch_vccnz .LBB0_326
	v_lshlrev_b64 v[28:29], 12, v[156:157]
	v_lshl_add_u64 v[28:29], v[142:143], 0, v[28:29]
	s_mov_b64 s[14:15], 0
	global_store_dwordx4 v[28:29], v[14:17], off offset:512

;   __device__ __forceinline__ void operator()(f32x4 (&acc)[2][2][4][2], int pm, int pn, int wr_, int wc_, int fr_, int fq_, bf16_t* shm, int tid) const {
;     ...
;             const int rl = ai * 128 + wr * 64 + m * 16 + fr, row = pm * 256 + rl;
;             const f2_t st = rst[rl];
;             f32x4 y = (acc[ai][bj][m][n] - st[0]) * st[1] * gg + bb;
;             if (outp) { *(f32x4*)(outp + (long)row * DM + col) = y; }
.LBB0_328:
	v_mov_b32_e32 v14, v186
	v_mov_b32_e32 v15, v187
	s_and_b64 vcc, exec, s[8:9]
	s_mov_b64 s[14:15], -1
	s_waitcnt lgkmcnt(0)
	v_sub_f32_e32 v17, v89, v14
	v_sub_f32_e32 v16, v88, v14
	v_sub_f32_e32 v29, v87, v14
	v_sub_f32_e32 v28, v86, v14
	v_pk_mul_f32 v[28:29], v[14:15], v[28:29] op_sel:[1,0]
	v_pk_mul_f32 v[14:15], v[14:15], v[16:17] op_sel:[1,0]
	s_nop 0
	v_pk_fma_f32 v[16:17], v[8:9], v[14:15], v[12:13]
	v_pk_fma_f32 v[14:15], v[6:7], v[28:29], v[10:11]
	s_cbranch_vccnz .LBB0_330
	v_lshlrev_b64 v[28:29], 12, v[18:19]
	v_lshl_add_u64 v[28:29], v[142:143], 0, v[28:29]
	s_mov_b64 s[14:15], 0
	global_store_dwordx4 v[28:29], v[14:17], off offset:512

;   __device__ __forceinline__ void operator()(f32x4 (&acc)[2][2][4][2], int pm, int pn, int wr_, int wc_, int fr_, int fq_, bf16_t* shm, int tid) const {
;     ...
;             const int rl = ai * 128 + wr * 64 + m * 16 + fr, row = pm * 256 + rl;
;             const f2_t st = rst[rl];
;             f32x4 y = (acc[ai][bj][m][n] - st[0]) * st[1] * gg + bb;
;             if (outp) { *(f32x4*)(outp + (long)row * DM + col) = y; }
.LBB0_332:
	v_mov_b32_e32 v14, v188
	v_mov_b32_e32 v15, v189
	s_and_b64 vcc, exec, s[8:9]
	s_mov_b64 s[14:15], -1
	s_waitcnt lgkmcnt(0)
	v_sub_f32_e32 v17, v93, v14
	v_sub_f32_e32 v16, v92, v14
	v_sub_f32_e32 v29, v91, v14
	v_sub_f32_e32 v28, v90, v14
	v_pk_mul_f32 v[28:29], v[14:15], v[28:29] op_sel:[1,0]
	v_pk_mul_f32 v[14:15], v[14:15], v[16:17] op_sel:[1,0]
	s_nop 0
	v_pk_fma_f32 v[16:17], v[8:9], v[14:15], v[12:13]
	v_pk_fma_f32 v[14:15], v[6:7], v[28:29], v[10:11]
	s_cbranch_vccnz .LBB0_334
	v_lshlrev_b64 v[28:29], 12, v[20:21]
	v_lshl_add_u64 v[28:29], v[142:143], 0, v[28:29]
	s_mov_b64 s[14:15], 0
	global_store_dwordx4 v[28:29], v[14:17], off offset:512

;   __device__ __forceinline__ void operator()(f32x4 (&acc)[2][2][4][2], int pm, int pn, int wr_, int wc_, int fr_, int fq_, bf16_t* shm, int tid) const {
;     ...
;             const int rl = ai * 128 + wr * 64 + m * 16 + fr, row = pm * 256 + rl;
;             const f2_t st = rst[rl];
;             f32x4 y = (acc[ai][bj][m][n] - st[0]) * st[1] * gg + bb;
;             if (outp) { *(f32x4*)(outp + (long)row * DM + col) = y; }
.LBB0_336:
	v_mov_b32_e32 v14, v190
	v_mov_b32_e32 v15, v191
	s_and_b64 vcc, exec, s[8:9]
	s_mov_b64 s[14:15], -1
	s_waitcnt lgkmcnt(0)
	v_sub_f32_e32 v17, v105, v14
	v_sub_f32_e32 v16, v104, v14
	v_sub_f32_e32 v29, v103, v14
	v_sub_f32_e32 v28, v102, v14
	v_pk_mul_f32 v[28:29], v[14:15], v[28:29] op_sel:[1,0]
	v_pk_mul_f32 v[14:15], v[14:15], v[16:17] op_sel:[1,0]
	v_pk_fma_f32 v[6:7], v[6:7], v[28:29], v[10:11]
	v_pk_fma_f32 v[8:9], v[8:9], v[14:15], v[12:13]
	s_cbranch_vccnz .LBB0_338
	v_lshlrev_b64 v[10:11], 12, v[22:23]
	v_lshl_add_u64 v[10:11], v[142:143], 0, v[10:11]
	s_mov_b64 s[14:15], 0
	global_store_dwordx4 v[10:11], v[6:9], off offset:512

;   __device__ __forceinline__ void operator()(f32x4 (&acc)[2][2][4][2], int pm, int pn, int wr_, int wc_, int fr_, int fq_, bf16_t* shm, int tid) const {
;     ...
;             const int rl = ai * 128 + wr * 64 + m * 16 + fr, row = pm * 256 + rl;
;             const f2_t st = rst[rl];
;             f32x4 y = (acc[ai][bj][m][n] - st[0]) * st[1] * gg + bb;
;             if (outp) { *(f32x4*)(outp + (long)row * DM + col) = y; }
.LBB0_343:
	v_mov_b32_e32 v14, v176
	v_mov_b32_e32 v15, v177
	s_and_b64 vcc, exec, s[8:9]
	s_mov_b64 s[0:1], -1
	s_waitcnt lgkmcnt(0)
	v_sub_f32_e32 v17, v101, v14
	v_sub_f32_e32 v16, v100, v14
	v_sub_f32_e32 v29, v99, v14
	v_sub_f32_e32 v28, v98, v14
	v_pk_mul_f32 v[28:29], v[14:15], v[28:29] op_sel:[1,0]
	v_pk_mul_f32 v[14:15], v[14:15], v[16:17] op_sel:[1,0]
	s_waitcnt vmcnt(0)
	v_pk_fma_f32 v[16:17], v[8:9], v[14:15], v[12:13]
	v_pk_fma_f32 v[14:15], v[6:7], v[28:29], v[10:11]
	s_cbranch_vccnz .LBB0_345
	v_lshlrev_b64 v[28:29], 12, v[148:149]
	v_lshl_add_u64 v[28:29], v[142:143], 0, v[28:29]
	s_mov_b64 s[0:1], 0
	global_store_dwordx4 v[28:29], v[14:17], off offset:576

;   __device__ __forceinline__ void operator()(f32x4 (&acc)[2][2][4][2], int pm, int pn, int wr_, int wc_, int fr_, int fq_, bf16_t* shm, int tid) const {
;     ...
;             const int rl = ai * 128 + wr * 64 + m * 16 + fr, row = pm * 256 + rl;
;             const f2_t st = rst[rl];
;             f32x4 y = (acc[ai][bj][m][n] - st[0]) * st[1] * gg + bb;
;             if (outp) { *(f32x4*)(outp + (long)row * DM + col) = y; }
.LBB0_347:
	v_mov_b32_e32 v14, v178
	v_mov_b32_e32 v15, v179
	s_and_b64 vcc, exec, s[8:9]
	s_mov_b64 s[0:1], -1
	s_waitcnt lgkmcnt(0)
	v_sub_f32_e32 v17, v109, v14
	v_sub_f32_e32 v16, v108, v14
	v_sub_f32_e32 v29, v107, v14
	v_sub_f32_e32 v28, v106, v14
	v_pk_mul_f32 v[28:29], v[14:15], v[28:29] op_sel:[1,0]
	v_pk_mul_f32 v[14:15], v[14:15], v[16:17] op_sel:[1,0]
	s_nop 0
	v_pk_fma_f32 v[16:17], v[8:9], v[14:15], v[12:13]
	v_pk_fma_f32 v[14:15], v[6:7], v[28:29], v[10:11]
	s_cbranch_vccnz .LBB0_349
	v_lshlrev_b64 v[28:29], 12, v[150:151]
	v_lshl_add_u64 v[28:29], v[142:143], 0, v[28:29]
	s_mov_b64 s[0:1], 0
	global_store_dwordx4 v[28:29], v[14:17], off offset:576

;   __device__ __forceinline__ void operator()(f32x4 (&acc)[2][2][4][2], int pm, int pn, int wr_, int wc_, int fr_, int fq_, bf16_t* shm, int tid) const {
;     ...
;             const int rl = ai * 128 + wr * 64 + m * 16 + fr, row = pm * 256 + rl;
;             const f2_t st = rst[rl];
;             f32x4 y = (acc[ai][bj][m][n] - st[0]) * st[1] * gg + bb;
;             if (outp) { *(f32x4*)(outp + (long)row * DM + col) = y; }
.LBB0_351:
	v_mov_b32_e32 v14, v180
	v_mov_b32_e32 v15, v181
	s_and_b64 vcc, exec, s[8:9]
	s_mov_b64 s[0:1], -1
	s_waitcnt lgkmcnt(0)
	v_sub_f32_e32 v17, v113, v14
	v_sub_f32_e32 v16, v112, v14
	v_sub_f32_e32 v29, v111, v14
	v_sub_f32_e32 v28, v110, v14
	v_pk_mul_f32 v[28:29], v[14:15], v[28:29] op_sel:[1,0]
	v_pk_mul_f32 v[14:15], v[14:15], v[16:17] op_sel:[1,0]
	s_nop 0
	v_pk_fma_f32 v[16:17], v[8:9], v[14:15], v[12:13]
	v_pk_fma_f32 v[14:15], v[6:7], v[28:29], v[10:11]
	s_cbranch_vccnz .LBB0_353
	v_lshlrev_b64 v[28:29], 12, v[152:153]
	v_lshl_add_u64 v[28:29], v[142:143], 0, v[28:29]
	s_mov_b64 s[0:1], 0
	global_store_dwordx4 v[28:29], v[14:17], off offset:576

;   __device__ __forceinline__ void operator()(f32x4 (&acc)[2][2][4][2], int pm, int pn, int wr_, int wc_, int fr_, int fq_, bf16_t* shm, int tid) const {
;     ...
;             const int rl = ai * 128 + wr * 64 + m * 16 + fr, row = pm * 256 + rl;
;             const f2_t st = rst[rl];
;             f32x4 y = (acc[ai][bj][m][n] - st[0]) * st[1] * gg + bb;
;             if (outp) { *(f32x4*)(outp + (long)row * DM + col) = y; }
.LBB0_355:
	v_mov_b32_e32 v14, v182
	v_mov_b32_e32 v15, v183
	s_and_b64 vcc, exec, s[8:9]
	s_mov_b64 s[0:1], -1
	s_waitcnt lgkmcnt(0)
	v_sub_f32_e32 v17, v117, v14
	v_sub_f32_e32 v16, v116, v14
	v_sub_f32_e32 v29, v115, v14
	v_sub_f32_e32 v28, v114, v14
	v_pk_mul_f32 v[28:29], v[14:15], v[28:29] op_sel:[1,0]
	v_pk_mul_f32 v[14:15], v[14:15], v[16:17] op_sel:[1,0]
	s_nop 0
	v_pk_fma_f32 v[16:17], v[8:9], v[14:15], v[12:13]
	v_pk_fma_f32 v[14:15], v[6:7], v[28:29], v[10:11]
	s_cbranch_vccnz .LBB0_357
	v_lshlrev_b64 v[28:29], 12, v[154:155]
	v_lshl_add_u64 v[28:29], v[142:143], 0, v[28:29]
	s_mov_b64 s[0:1], 0
	global_store_dwordx4 v[28:29], v[14:17], off offset:576

;   __device__ __forceinline__ void operator()(f32x4 (&acc)[2][2][4][2], int pm, int pn, int wr_, int wc_, int fr_, int fq_, bf16_t* shm, int tid) const {
;     ...
;             const int rl = ai * 128 + wr * 64 + m * 16 + fr, row = pm * 256 + rl;
;             const f2_t st = rst[rl];
;             f32x4 y = (acc[ai][bj][m][n] - st[0]) * st[1] * gg + bb;
;             if (outp) { *(f32x4*)(outp + (long)row * DM + col) = y; }
.LBB0_359:
	v_mov_b32_e32 v14, v184
	v_mov_b32_e32 v15, v185
	s_and_b64 vcc, exec, s[8:9]
	s_mov_b64 s[0:1], -1
	s_waitcnt lgkmcnt(0)
	v_sub_f32_e32 v17, v125, v14
	v_sub_f32_e32 v16, v124, v14
	v_sub_f32_e32 v29, v123, v14
	v_sub_f32_e32 v28, v122, v14
	v_pk_mul_f32 v[28:29], v[14:15], v[28:29] op_sel:[1,0]
	v_pk_mul_f32 v[14:15], v[14:15], v[16:17] op_sel:[1,0]
	s_nop 0
	v_pk_fma_f32 v[16:17], v[8:9], v[14:15], v[12:13]
	v_pk_fma_f32 v[14:15], v[6:7], v[28:29], v[10:11]
	s_cbranch_vccnz .LBB0_361
	v_lshlrev_b64 v[28:29], 12, v[156:157]
	v_lshl_add_u64 v[28:29], v[142:143], 0, v[28:29]
	s_mov_b64 s[0:1], 0
	global_store_dwordx4 v[28:29], v[14:17], off offset:576

;   __device__ __forceinline__ void operator()(f32x4 (&acc)[2][2][4][2], int pm, int pn, int wr_, int wc_, int fr_, int fq_, bf16_t* shm, int tid) const {
;     ...
;             const int rl = ai * 128 + wr * 64 + m * 16 + fr, row = pm * 256 + rl;
;             const f2_t st = rst[rl];
;             f32x4 y = (acc[ai][bj][m][n] - st[0]) * st[1] * gg + bb;
;             if (outp) { *(f32x4*)(outp + (long)row * DM + col) = y; }
.LBB0_363:
	v_mov_b32_e32 v14, v186
	v_mov_b32_e32 v15, v187
	s_and_b64 vcc, exec, s[8:9]
	s_mov_b64 s[0:1], -1
	s_waitcnt lgkmcnt(0)
	v_sub_f32_e32 v17, v129, v14
	v_sub_f32_e32 v16, v128, v14
	v_sub_f32_e32 v29, v127, v14
	v_sub_f32_e32 v28, v126, v14
	v_pk_mul_f32 v[28:29], v[14:15], v[28:29] op_sel:[1,0]
	v_pk_mul_f32 v[14:15], v[14:15], v[16:17] op_sel:[1,0]
	s_nop 0
	v_pk_fma_f32 v[16:17], v[8:9], v[14:15], v[12:13]
	v_pk_fma_f32 v[14:15], v[6:7], v[28:29], v[10:11]
	s_cbranch_vccnz .LBB0_365
	v_lshlrev_b64 v[28:29], 12, v[18:19]
	v_lshl_add_u64 v[28:29], v[142:143], 0, v[28:29]
	s_mov_b64 s[0:1], 0
	global_store_dwordx4 v[28:29], v[14:17], off offset:576

;   __device__ __forceinline__ void operator()(f32x4 (&acc)[2][2][4][2], int pm, int pn, int wr_, int wc_, int fr_, int fq_, bf16_t* shm, int tid) const {
;     ...
;             const int rl = ai * 128 + wr * 64 + m * 16 + fr, row = pm * 256 + rl;
;             const f2_t st = rst[rl];
;             f32x4 y = (acc[ai][bj][m][n] - st[0]) * st[1] * gg + bb;
;             if (outp) { *(f32x4*)(outp + (long)row * DM + col) = y; }
.LBB0_367:
	v_mov_b32_e32 v14, v188
	v_mov_b32_e32 v15, v189
	s_and_b64 vcc, exec, s[8:9]
	s_mov_b64 s[0:1], -1
	s_waitcnt lgkmcnt(0)
	v_sub_f32_e32 v17, v121, v14
	v_sub_f32_e32 v16, v120, v14
	v_sub_f32_e32 v19, v119, v14
	v_sub_f32_e32 v18, v118, v14
	v_pk_mul_f32 v[18:19], v[14:15], v[18:19] op_sel:[1,0]
	v_pk_mul_f32 v[14:15], v[14:15], v[16:17] op_sel:[1,0]
	s_nop 0
	v_pk_fma_f32 v[16:17], v[8:9], v[14:15], v[12:13]
	v_pk_fma_f32 v[14:15], v[6:7], v[18:19], v[10:11]
	s_cbranch_vccnz .LBB0_369
	v_lshlrev_b64 v[18:19], 12, v[20:21]
	v_lshl_add_u64 v[18:19], v[142:143], 0, v[18:19]
	s_mov_b64 s[0:1], 0
	global_store_dwordx4 v[18:19], v[14:17], off offset:576

;   __device__ __forceinline__ void operator()(f32x4 (&acc)[2][2][4][2], int pm, int pn, int wr_, int wc_, int fr_, int fq_, bf16_t* shm, int tid) const {
;     ...
;             const int rl = ai * 128 + wr * 64 + m * 16 + fr, row = pm * 256 + rl;
;             const f2_t st = rst[rl];
;             f32x4 y = (acc[ai][bj][m][n] - st[0]) * st[1] * gg + bb;
;             if (outp) { *(f32x4*)(outp + (long)row * DM + col) = y; }
.LBB0_371:
	v_mov_b32_e32 v14, v190
	v_mov_b32_e32 v15, v191
	s_and_b64 vcc, exec, s[8:9]
	s_mov_b64 s[0:1], -1
	s_waitcnt lgkmcnt(0)
	v_sub_f32_e32 v17, v97, v14
	v_sub_f32_e32 v16, v96, v14
	v_sub_f32_e32 v19, v95, v14
	v_sub_f32_e32 v18, v94, v14
	v_pk_mul_f32 v[18:19], v[14:15], v[18:19] op_sel:[1,0]
	v_pk_mul_f32 v[14:15], v[14:15], v[16:17] op_sel:[1,0]
	v_pk_fma_f32 v[6:7], v[6:7], v[18:19], v[10:11]
	v_pk_fma_f32 v[8:9], v[8:9], v[14:15], v[12:13]
	s_cbranch_vccnz .LBB0_373
	v_lshlrev_b64 v[10:11], 12, v[22:23]
	v_lshl_add_u64 v[10:11], v[142:143], 0, v[10:11]
	s_mov_b64 s[0:1], 0
	global_store_dwordx4 v[10:11], v[6:9], off offset:576

; __device__ __forceinline__ unsigned pk2(float lo, float hi) { const f2_t v = {lo, hi}; return __builtin_bit_cast(unsigned, __builtin_convertvector(v, bf2_t)); }
;   __device__ __forceinline__ void operator()(f32x4 (&acc)[2][2][4][2], int pm, int pn, int wr_, int wc_, int fr_, int fq_, bf16_t* shm, int tid) const {
;     ...
; #pragma unroll
;     for (int bj = 0; bj < 2; ++bj)
; #pragma unroll
;       for (int n = 0; n < 2; ++n) {
;         asm volatile("" ::: "memory");
;         const int col = pn * 256 + bj * 128 + wc * 32 + n * 16 + fq * 4;
;         const f32x4 gg = *(const f32x4*)(ng + col), bb = *(const f32x4*)(nb + col);
;         f32x4 sh = {0.f, 0.f, 0.f, 0.f}, sc = {0.f, 0.f, 0.f, 0.f};
;         if (!outp) { sh = *(const f32x4*)(msh + bio + col); sc = *(const f32x4*)(msc + bio + col); }
; #pragma unroll
;         for (int ai = 0; ai < 2; ++ai)
; #pragma unroll
;           for (int m = 0; m < 4; ++m) {
;             const int rl = ai * 128 + wr * 64 + m * 16 + fr, row = pm * 256 + rl;
;             const f2_t st = rst[rl];
;             f32x4 y = (acc[ai][bj][m][n] - st[0]) * st[1] * gg + bb;
;             if (outp) { *(f32x4*)(outp + (long)row * DM + col) = y; }
;             else {
;               y = y * (sc + 1.f) + sh;
;               u32x2 w; w.x = pk2(y[0], y[1]); w.y = pk2(y[2], y[3]);
;               *(u32x2*)(H + (long)row * DM + col) = w;
;               if (HA && (rl == 0 || rl == 255)) *(u32x2*)(HA + (long)(pm * 2 + (rl == 255)) * DM + col) = w;
;             }
;           }
.LBB0_579:
	s_or_b64 exec, exec, s[0:1]
	s_add_u32 s0, s29, s6
	s_addc_u32 s1, s30, s7
	s_add_u32 s6, s24, s6
	s_addc_u32 s7, s28, s7
	s_waitcnt lgkmcnt(0)
	s_barrier
	v_lshl_add_u64 v[144:145], s[78:79], 0, v[146:147]
	v_lshl_add_u64 v[148:149], s[42:43], 0, v[146:147]
	v_lshl_add_u64 v[150:151], s[0:1], 0, v[146:147]
	v_lshl_add_u64 v[146:147], s[6:7], 0, v[146:147]
	global_load_dwordx4 v[130:133], v[144:145], off
	global_load_dwordx4 v[134:137], v[148:149], off
	global_load_dwordx4 v[138:141], v[146:147], off
	global_load_dwordx4 v[154:157], v[150:151], off
	v_readlane_b32 s44, v252, 20
	v_lshlrev_b32_e32 v0, 1, v0
	v_readlane_b32 s50, v252, 26
	v_readlane_b32 s51, v252, 27
	v_readlane_b32 s54, v252, 30
	v_readlane_b32 s55, v252, 31
	v_add_u32_e32 v158, s82, v160
	v_ashrrev_i32_e32 v159, 31, v158
	v_lshl_add_u64 v[142:143], s[54:55], 0, v[0:1]
	v_readlane_b32 s0, v251, 7
	v_cmp_eq_u32_e32 vcc, 0, v160
	v_readlane_b32 s1, v251, 8
	s_lshl_b32 s4, s4, 1
	s_and_b64 s[6:7], s[0:1], vcc
	v_readlane_b32 s45, v252, 21
	v_readlane_b32 s46, v252, 22
	v_readlane_b32 s47, v252, 23
	v_readlane_b32 s48, v252, 24
	v_readlane_b32 s49, v252, 25
	v_readlane_b32 s52, v252, 28
	v_readlane_b32 s53, v252, 29
	v_readlane_b32 s56, v252, 32
	v_readlane_b32 s57, v252, 33
	v_readlane_b32 s58, v252, 34
	v_readlane_b32 s59, v252, 35
	s_waitcnt vmcnt(0)
	v_pk_add_f32 v[152:153], v[156:157], 1.0 op_sel_hi:[1,0]
	v_lshl_add_u64 v[156:157], s[50:51], 0, v[0:1]
	v_lshl_add_u32 v0, v160, 3, 16
	v_add_u32_e32 v0, 0x22000, v0
	ds_read_b64 v[176:177], v0
	ds_read_b64 v[178:179], v0 offset:128
	ds_read_b64 v[180:181], v0 offset:256
	ds_read_b64 v[182:183], v0 offset:384
	ds_read_b64 v[184:185], v0 offset:1024
	ds_read_b64 v[186:187], v0 offset:1152
	ds_read_b64 v[188:189], v0 offset:1280
	ds_read_b64 v[190:191], v0 offset:1408
	s_waitcnt lgkmcnt(0)
	v_mov_b32_e32 v162, v176
	v_mov_b32_e32 v163, v177
	v_pk_add_f32 v[154:155], v[154:155], 1.0 op_sel_hi:[1,0]
	s_waitcnt lgkmcnt(0)
	v_sub_f32_e32 v127, v127, v162
	v_sub_f32_e32 v126, v126, v162
	v_sub_f32_e32 v129, v129, v162
	v_sub_f32_e32 v128, v128, v162
	v_pk_mul_f32 v[126:127], v[162:163], v[126:127] op_sel:[1,0]
	v_pk_mul_f32 v[128:129], v[162:163], v[128:129] op_sel:[1,0]
	v_pk_fma_f32 v[126:127], v[130:131], v[126:127], v[134:135]
	v_pk_fma_f32 v[128:129], v[132:133], v[128:129], v[136:137]
	v_pk_fma_f32 v[126:127], v[154:155], v[126:127], v[138:139]
	v_pk_fma_f32 v[162:163], v[152:153], v[128:129], v[140:141]
	v_cvt_pk_bf16_f32 v128, v126, v127
	v_lshlrev_b64 v[126:127], 11, v[158:159]
	v_cvt_pk_bf16_f32 v129, v162, v163
	v_lshl_add_u64 v[126:127], v[156:157], 0, v[126:127]
	global_store_dwordx2 v[126:127], v[128:129], off
	s_and_saveexec_b64 s[0:1], s[6:7]
	s_cbranch_execz .LBB0_581
	s_ashr_i32 s5, s4, 31
	s_lshl_b64 s[8:9], s[4:5], 11
	v_lshl_add_u64 v[162:163], v[142:143], 0, s[8:9]
	global_store_dwordx2 v[162:163], v[128:129], off
.LBB0_581:
	s_or_b64 exec, exec, s[0:1]
	v_or_b32_e32 v129, 16, v160
	s_add_i32 s0, 16, 0x22000
	v_lshl_add_u32 v159, v129, 3, s0
	v_mov_b32_e32 v162, v178
	v_mov_b32_e32 v163, v179
	v_add_u32_e32 v128, s82, v129
	v_ashrrev_i32_e32 v129, 31, v128
	s_waitcnt lgkmcnt(0)
	v_sub_f32_e32 v113, v113, v162
	v_sub_f32_e32 v112, v112, v162
	v_pk_mul_f32 v[112:113], v[162:163], v[112:113] op_sel:[1,0]
	v_sub_f32_e32 v111, v111, v162
	v_sub_f32_e32 v110, v110, v162
	v_pk_fma_f32 v[112:113], v[132:133], v[112:113], v[136:137]
	v_pk_mul_f32 v[110:111], v[162:163], v[110:111] op_sel:[1,0]
	v_pk_fma_f32 v[112:113], v[152:153], v[112:113], v[140:141]
	v_pk_fma_f32 v[110:111], v[130:131], v[110:111], v[134:135]
	v_cvt_pk_bf16_f32 v163, v112, v113
	v_or_b32_e32 v113, 32, v160
	v_pk_fma_f32 v[110:111], v[154:155], v[110:111], v[138:139]
	v_lshl_add_u32 v161, v113, 3, s0
	v_cvt_pk_bf16_f32 v162, v110, v111
	v_lshlrev_b64 v[110:111], 11, v[128:129]
	v_mov_b32_e32 v128, v180
	v_mov_b32_e32 v129, v181
	v_lshl_add_u64 v[110:111], v[156:157], 0, v[110:111]
	v_add_u32_e32 v112, s82, v113
	global_store_dwordx2 v[110:111], v[162:163], off
	v_ashrrev_i32_e32 v113, 31, v112
	s_waitcnt lgkmcnt(0)
	v_sub_f32_e32 v97, v97, v128
	v_sub_f32_e32 v96, v96, v128
	v_pk_mul_f32 v[96:97], v[128:129], v[96:97] op_sel:[1,0]
	v_sub_f32_e32 v95, v95, v128
	v_sub_f32_e32 v94, v94, v128
	v_pk_fma_f32 v[96:97], v[132:133], v[96:97], v[136:137]
	v_pk_mul_f32 v[94:95], v[128:129], v[94:95] op_sel:[1,0]
	v_pk_fma_f32 v[96:97], v[152:153], v[96:97], v[140:141]
	v_pk_fma_f32 v[94:95], v[130:131], v[94:95], v[134:135]
	v_cvt_pk_bf16_f32 v129, v96, v97
	v_or_b32_e32 v97, 48, v160
	v_pk_fma_f32 v[94:95], v[154:155], v[94:95], v[138:139]
	v_lshl_add_u32 v162, v97, 3, s0
	v_cvt_pk_bf16_f32 v128, v94, v95
	v_lshlrev_b64 v[94:95], 11, v[112:113]
	v_mov_b32_e32 v112, v182
	v_mov_b32_e32 v113, v183
	v_add_u32_e32 v96, s82, v97
	s_movk_i32 s0, 0xcf
	v_ashrrev_i32_e32 v97, 31, v96
	v_cmp_eq_u32_e32 vcc, s0, v160
	s_waitcnt lgkmcnt(0)
	v_sub_f32_e32 v3, v3, v112
	v_sub_f32_e32 v2, v2, v112
	v_sub_f32_e32 v5, v5, v112
	v_sub_f32_e32 v4, v4, v112
	v_pk_mul_f32 v[4:5], v[112:113], v[4:5] op_sel:[1,0]
	v_pk_mul_f32 v[2:3], v[112:113], v[2:3] op_sel:[1,0]
	v_pk_fma_f32 v[4:5], v[132:133], v[4:5], v[136:137]
	v_pk_fma_f32 v[2:3], v[130:131], v[2:3], v[134:135]
	v_pk_fma_f32 v[4:5], v[152:153], v[4:5], v[140:141]
	v_pk_fma_f32 v[2:3], v[154:155], v[2:3], v[138:139]
	v_readlane_b32 s0, v251, 7
	v_cvt_pk_bf16_f32 v2, v2, v3
	v_cvt_pk_bf16_f32 v3, v4, v5
	v_lshlrev_b64 v[4:5], 11, v[96:97]
	v_readlane_b32 s1, v251, 8
	v_lshl_add_u64 v[94:95], v[156:157], 0, v[94:95]
	v_lshl_add_u64 v[96:97], v[156:157], 0, v[4:5]
	s_and_b64 s[8:9], vcc, s[0:1]
	global_store_dwordx2 v[94:95], v[128:129], off
	global_store_dwordx2 v[96:97], v[2:3], off
	s_and_saveexec_b64 s[0:1], s[8:9]
	s_cbranch_execz .LBB0_583
	s_or_b32 s12, s4, 1
	s_ashr_i32 s13, s12, 31
	s_lshl_b64 s[12:13], s[12:13], 11
	v_lshl_add_u64 v[4:5], v[142:143], 0, s[12:13]
	global_store_dwordx2 v[4:5], v[2:3], off
; __device__ __forceinline__ unsigned pk2(float lo, float hi) { const f2_t v = {lo, hi}; return __builtin_bit_cast(unsigned, __builtin_convertvector(v, bf2_t)); }
;   __device__ __forceinline__ void operator()(f32x4 (&acc)[2][2][4][2], int pm, int pn, int wr_, int wc_, int fr_, int fq_, bf16_t* shm, int tid) const {
;     ...
;       for (int n = 0; n < 2; ++n) {
;         asm volatile("" ::: "memory");
;         const int col = pn * 256 + bj * 128 + wc * 32 + n * 16 + fq * 4;
;         const f32x4 gg = *(const f32x4*)(ng + col), bb = *(const f32x4*)(nb + col);
;         f32x4 sh = {0.f, 0.f, 0.f, 0.f}, sc = {0.f, 0.f, 0.f, 0.f};
;         if (!outp) { sh = *(const f32x4*)(msh + bio + col); sc = *(const f32x4*)(msc + bio + col); }
; #pragma unroll
;         for (int ai = 0; ai < 2; ++ai)
; #pragma unroll
;           for (int m = 0; m < 4; ++m) {
;             const int rl = ai * 128 + wr * 64 + m * 16 + fr, row = pm * 256 + rl;
;             const f2_t st = rst[rl];
;             f32x4 y = (acc[ai][bj][m][n] - st[0]) * st[1] * gg + bb;
;             if (outp) { *(f32x4*)(outp + (long)row * DM + col) = y; }
;             else {
;               y = y * (sc + 1.f) + sh;
;               u32x2 w; w.x = pk2(y[0], y[1]); w.y = pk2(y[2], y[3]);
;               *(u32x2*)(H + (long)row * DM + col) = w;
;               if (HA && (rl == 0 || rl == 255)) *(u32x2*)(HA + (long)(pm * 2 + (rl == 255)) * DM + col) = w;
;             }
;           }
.LBB0_583:
	s_or_b64 exec, exec, s[0:1]
	v_mov_b32_e32 v2, v184
	v_mov_b32_e32 v3, v185
	v_add_u32_e32 v4, 0x80, v158
	s_movk_i32 s0, 0xff80
	v_ashrrev_i32_e32 v5, 31, v4
	v_cmp_eq_u32_e32 vcc, s0, v160
	s_waitcnt lgkmcnt(0)
	v_sub_f32_e32 v7, v7, v2
	v_sub_f32_e32 v6, v6, v2
	v_sub_f32_e32 v9, v9, v2
	v_sub_f32_e32 v8, v8, v2
	v_pk_mul_f32 v[8:9], v[2:3], v[8:9] op_sel:[1,0]
	v_pk_mul_f32 v[2:3], v[2:3], v[6:7] op_sel:[1,0]
	v_pk_fma_f32 v[6:7], v[132:133], v[8:9], v[136:137]
	v_pk_fma_f32 v[2:3], v[130:131], v[2:3], v[134:135]
	v_readlane_b32 s0, v251, 7
	v_pk_fma_f32 v[6:7], v[152:153], v[6:7], v[140:141]
	v_pk_fma_f32 v[2:3], v[154:155], v[2:3], v[138:139]
	v_lshlrev_b64 v[4:5], 11, v[4:5]
	v_readlane_b32 s1, v251, 8
	v_cvt_pk_bf16_f32 v2, v2, v3
	v_cvt_pk_bf16_f32 v3, v6, v7
	v_lshl_add_u64 v[112:113], v[156:157], 0, v[4:5]
	s_and_b64 s[82:83], s[0:1], vcc
	global_store_dwordx2 v[112:113], v[2:3], off
	s_and_saveexec_b64 s[0:1], s[82:83]
	s_cbranch_execz .LBB0_585
	s_ashr_i32 s5, s4, 31
	s_lshl_b64 s[12:13], s[4:5], 11
	v_lshl_add_u64 v[4:5], v[142:143], 0, s[12:13]
	global_store_dwordx2 v[4:5], v[2:3], off
.LBB0_585:
	s_or_b64 exec, exec, s[0:1]
	v_mov_b32_e32 v2, v186
	v_mov_b32_e32 v3, v187
	v_mov_b32_e32 v4, v188
	v_mov_b32_e32 v5, v189
	v_add_u32_e32 v6, 0x90, v158
	v_ashrrev_i32_e32 v7, 31, v6
	v_lshlrev_b64 v[6:7], 11, v[6:7]
	v_lshl_add_u64 v[128:129], v[156:157], 0, v[6:7]
	s_waitcnt lgkmcnt(0)
	v_sub_f32_e32 v9, v15, v2
	v_sub_f32_e32 v8, v14, v2
	v_sub_f32_e32 v15, v17, v2
	v_sub_f32_e32 v14, v16, v2
	v_pk_mul_f32 v[14:15], v[2:3], v[14:15] op_sel:[1,0]
	v_pk_mul_f32 v[2:3], v[2:3], v[8:9] op_sel:[1,0]
	v_pk_fma_f32 v[8:9], v[132:133], v[14:15], v[136:137]
	v_pk_fma_f32 v[2:3], v[130:131], v[2:3], v[134:135]
	v_pk_fma_f32 v[8:9], v[152:153], v[8:9], v[140:141]
	v_pk_fma_f32 v[2:3], v[154:155], v[2:3], v[138:139]
	v_sub_f32_e32 v7, v31, v4
	v_cvt_pk_bf16_f32 v2, v2, v3
	v_cvt_pk_bf16_f32 v3, v8, v9
	v_sub_f32_e32 v6, v30, v4
	v_sub_f32_e32 v9, v33, v4
	v_sub_f32_e32 v8, v32, v4
	v_pk_mul_f32 v[8:9], v[4:5], v[8:9] op_sel:[1,0]
	v_pk_mul_f32 v[4:5], v[4:5], v[6:7] op_sel:[1,0]
	v_pk_fma_f32 v[6:7], v[132:133], v[8:9], v[136:137]
	v_pk_fma_f32 v[4:5], v[130:131], v[4:5], v[134:135]
	v_pk_fma_f32 v[6:7], v[152:153], v[6:7], v[140:141]
	v_pk_fma_f32 v[4:5], v[154:155], v[4:5], v[138:139]
	global_store_dwordx2 v[128:129], v[2:3], off
	v_cvt_pk_bf16_f32 v4, v4, v5
	v_cvt_pk_bf16_f32 v5, v6, v7
	v_mov_b32_e32 v6, v190
	v_mov_b32_e32 v7, v191
	v_add_u32_e32 v2, 0xa0, v158
	v_ashrrev_i32_e32 v3, 31, v2
	v_lshlrev_b64 v[2:3], 11, v[2:3]
	v_lshl_add_u64 v[30:31], v[156:157], 0, v[2:3]
	s_waitcnt lgkmcnt(0)
	v_sub_f32_e32 v3, v55, v6
	v_sub_f32_e32 v2, v54, v6
	v_sub_f32_e32 v9, v57, v6
	v_sub_f32_e32 v8, v56, v6
	global_store_dwordx2 v[30:31], v[4:5], off
	v_add_u32_e32 v4, 0xb0, v158
	v_pk_mul_f32 v[8:9], v[6:7], v[8:9] op_sel:[1,0]
	v_pk_mul_f32 v[2:3], v[6:7], v[2:3] op_sel:[1,0]
	s_movk_i32 s0, 0x4f
	v_pk_fma_f32 v[2:3], v[130:131], v[2:3], v[134:135]
	v_pk_fma_f32 v[6:7], v[132:133], v[8:9], v[136:137]
	v_ashrrev_i32_e32 v5, 31, v4
	v_cmp_eq_u32_e32 vcc, s0, v160
	v_readlane_b32 s0, v251, 7
	v_pk_fma_f32 v[6:7], v[152:153], v[6:7], v[140:141]
	v_pk_fma_f32 v[2:3], v[154:155], v[2:3], v[138:139]
	v_lshlrev_b64 v[4:5], 11, v[4:5]
	v_readlane_b32 s1, v251, 8
	v_cvt_pk_bf16_f32 v2, v2, v3
	v_cvt_pk_bf16_f32 v3, v6, v7
	v_lshl_add_u64 v[32:33], v[156:157], 0, v[4:5]
	s_and_b64 vcc, s[0:1], vcc
	global_store_dwordx2 v[32:33], v[2:3], off
	s_and_saveexec_b64 s[0:1], vcc
	s_cbranch_execz .LBB0_587
	s_or_b32 s12, s4, 1
	s_ashr_i32 s13, s12, 31
	s_lshl_b64 s[12:13], s[12:13], 11
	v_lshl_add_u64 v[4:5], v[142:143], 0, s[12:13]
	global_store_dwordx2 v[4:5], v[2:3], off
.LBB0_587:
	s_or_b64 exec, exec, s[0:1]
	global_load_dwordx4 v[130:133], v[150:151], off offset:64
	global_load_dwordx4 v[2:5], v[144:145], off offset:64
	global_load_dwordx4 v[14:17], v[148:149], off offset:64
	global_load_dwordx4 v[6:9], v[146:147], off offset:64
	v_mov_b32_e32 v54, v176
	v_mov_b32_e32 v55, v177
	s_waitcnt lgkmcnt(0)
	v_sub_f32_e32 v57, v83, v54
	v_sub_f32_e32 v56, v82, v54
	v_sub_f32_e32 v83, v85, v54
	v_sub_f32_e32 v82, v84, v54
	v_pk_mul_f32 v[82:83], v[54:55], v[82:83] op_sel:[1,0]
	v_pk_mul_f32 v[84:85], v[54:55], v[56:57] op_sel:[1,0]
	s_waitcnt vmcnt(3)
	v_pk_add_f32 v[54:55], v[132:133], 1.0 op_sel_hi:[1,0]
	v_pk_add_f32 v[56:57], v[130:131], 1.0 op_sel_hi:[1,0]
	s_waitcnt vmcnt(1)
	v_pk_fma_f32 v[84:85], v[2:3], v[84:85], v[14:15]
	v_pk_fma_f32 v[82:83], v[4:5], v[82:83], v[16:17]
	s_waitcnt vmcnt(0)
	v_pk_fma_f32 v[130:131], v[54:55], v[82:83], v[8:9]
	v_pk_fma_f32 v[82:83], v[56:57], v[84:85], v[6:7]
	s_nop 0
	v_cvt_pk_bf16_f32 v82, v82, v83
	v_cvt_pk_bf16_f32 v83, v130, v131
	global_store_dwordx2 v[126:127], v[82:83], off offset:32
	s_and_saveexec_b64 s[0:1], s[6:7]
	s_cbranch_execz .LBB0_589
	s_ashr_i32 s5, s4, 31
	s_lshl_b64 s[12:13], s[4:5], 11
	v_lshl_add_u64 v[84:85], v[142:143], 0, s[12:13]
	global_store_dwordx2 v[84:85], v[82:83], off offset:32
; __device__ __forceinline__ unsigned pk2(float lo, float hi) { const f2_t v = {lo, hi}; return __builtin_bit_cast(unsigned, __builtin_convertvector(v, bf2_t)); }
;   __device__ __forceinline__ void operator()(f32x4 (&acc)[2][2][4][2], int pm, int pn, int wr_, int wc_, int fr_, int fq_, bf16_t* shm, int tid) const {
;     ...
;       for (int n = 0; n < 2; ++n) {
;         asm volatile("" ::: "memory");
;         const int col = pn * 256 + bj * 128 + wc * 32 + n * 16 + fq * 4;
;         const f32x4 gg = *(const f32x4*)(ng + col), bb = *(const f32x4*)(nb + col);
;         f32x4 sh = {0.f, 0.f, 0.f, 0.f}, sc = {0.f, 0.f, 0.f, 0.f};
;         if (!outp) { sh = *(const f32x4*)(msh + bio + col); sc = *(const f32x4*)(msc + bio + col); }
; #pragma unroll
;         for (int ai = 0; ai < 2; ++ai)
; #pragma unroll
;           for (int m = 0; m < 4; ++m) {
;             const int rl = ai * 128 + wr * 64 + m * 16 + fr, row = pm * 256 + rl;
;             const f2_t st = rst[rl];
;             f32x4 y = (acc[ai][bj][m][n] - st[0]) * st[1] * gg + bb;
;             if (outp) { *(f32x4*)(outp + (long)row * DM + col) = y; }
;             else {
;               y = y * (sc + 1.f) + sh;
;               u32x2 w; w.x = pk2(y[0], y[1]); w.y = pk2(y[2], y[3]);
;               *(u32x2*)(H + (long)row * DM + col) = w;
;               if (HA && (rl == 0 || rl == 255)) *(u32x2*)(HA + (long)(pm * 2 + (rl == 255)) * DM + col) = w;
;             }
;           }
.LBB0_589:
	s_or_b64 exec, exec, s[0:1]
	v_mov_b32_e32 v82, v178
	v_mov_b32_e32 v83, v179
	s_waitcnt lgkmcnt(0)
	v_sub_f32_e32 v85, v87, v82
	v_sub_f32_e32 v84, v86, v82
	v_sub_f32_e32 v87, v89, v82
	v_sub_f32_e32 v86, v88, v82
	v_pk_mul_f32 v[86:87], v[82:83], v[86:87] op_sel:[1,0]
	v_pk_mul_f32 v[82:83], v[82:83], v[84:85] op_sel:[1,0]
	v_pk_fma_f32 v[84:85], v[4:5], v[86:87], v[16:17]
	v_pk_fma_f32 v[82:83], v[2:3], v[82:83], v[14:15]
	v_pk_fma_f32 v[84:85], v[54:55], v[84:85], v[8:9]
	v_pk_fma_f32 v[82:83], v[56:57], v[82:83], v[6:7]
	s_nop 0
	v_cvt_pk_bf16_f32 v82, v82, v83
	v_cvt_pk_bf16_f32 v83, v84, v85
	global_store_dwordx2 v[110:111], v[82:83], off offset:32
	v_mov_b32_e32 v82, v180
	v_mov_b32_e32 v83, v181
	s_waitcnt lgkmcnt(0)
	v_sub_f32_e32 v79, v79, v82
	v_sub_f32_e32 v78, v78, v82
	v_sub_f32_e32 v81, v81, v82
	v_sub_f32_e32 v80, v80, v82
	v_pk_mul_f32 v[80:81], v[82:83], v[80:81] op_sel:[1,0]
	v_pk_mul_f32 v[78:79], v[82:83], v[78:79] op_sel:[1,0]
	v_pk_fma_f32 v[80:81], v[4:5], v[80:81], v[16:17]
	v_pk_fma_f32 v[78:79], v[2:3], v[78:79], v[14:15]
	v_pk_fma_f32 v[80:81], v[54:55], v[80:81], v[8:9]
	v_pk_fma_f32 v[78:79], v[56:57], v[78:79], v[6:7]
	s_nop 0
	v_cvt_pk_bf16_f32 v78, v78, v79
	v_cvt_pk_bf16_f32 v79, v80, v81
	global_store_dwordx2 v[94:95], v[78:79], off offset:32
	v_mov_b32_e32 v78, v182
	v_mov_b32_e32 v79, v183
	s_waitcnt lgkmcnt(0)
	v_sub_f32_e32 v11, v11, v78
	v_sub_f32_e32 v10, v10, v78
	v_sub_f32_e32 v13, v13, v78
	v_sub_f32_e32 v12, v12, v78
	v_pk_mul_f32 v[12:13], v[78:79], v[12:13] op_sel:[1,0]
	v_pk_mul_f32 v[10:11], v[78:79], v[10:11] op_sel:[1,0]
	v_pk_fma_f32 v[12:13], v[4:5], v[12:13], v[16:17]
	v_pk_fma_f32 v[10:11], v[2:3], v[10:11], v[14:15]
	v_pk_fma_f32 v[12:13], v[54:55], v[12:13], v[8:9]
	v_pk_fma_f32 v[10:11], v[56:57], v[10:11], v[6:7]
	s_nop 0
	v_cvt_pk_bf16_f32 v10, v10, v11
	v_cvt_pk_bf16_f32 v11, v12, v13
	global_store_dwordx2 v[96:97], v[10:11], off offset:32
	s_and_saveexec_b64 s[0:1], s[8:9]
	s_cbranch_execz .LBB0_591
	s_or_b32 s12, s4, 1
	s_ashr_i32 s13, s12, 31
	s_lshl_b64 s[12:13], s[12:13], 11
	v_lshl_add_u64 v[12:13], v[142:143], 0, s[12:13]
	global_store_dwordx2 v[12:13], v[10:11], off offset:32
.LBB0_591:
	s_or_b64 exec, exec, s[0:1]
	v_mov_b32_e32 v10, v184
	v_mov_b32_e32 v11, v185
	s_waitcnt lgkmcnt(0)
	v_sub_f32_e32 v13, v19, v10
	v_sub_f32_e32 v12, v18, v10
	v_sub_f32_e32 v19, v21, v10
	v_sub_f32_e32 v18, v20, v10
	v_pk_mul_f32 v[18:19], v[10:11], v[18:19] op_sel:[1,0]
	v_pk_mul_f32 v[10:11], v[10:11], v[12:13] op_sel:[1,0]
	v_pk_fma_f32 v[12:13], v[4:5], v[18:19], v[16:17]
	v_pk_fma_f32 v[10:11], v[2:3], v[10:11], v[14:15]
	v_pk_fma_f32 v[12:13], v[54:55], v[12:13], v[8:9]
	v_pk_fma_f32 v[10:11], v[56:57], v[10:11], v[6:7]
	s_nop 0
	v_cvt_pk_bf16_f32 v10, v10, v11
	v_cvt_pk_bf16_f32 v11, v12, v13
	global_store_dwordx2 v[112:113], v[10:11], off offset:32
	s_and_saveexec_b64 s[0:1], s[82:83]
	s_cbranch_execz .LBB0_593
	s_ashr_i32 s5, s4, 31
	s_lshl_b64 s[12:13], s[4:5], 11
	v_lshl_add_u64 v[12:13], v[142:143], 0, s[12:13]
	global_store_dwordx2 v[12:13], v[10:11], off offset:32
.LBB0_593:
	s_or_b64 exec, exec, s[0:1]
	v_mov_b32_e32 v10, v186
	v_mov_b32_e32 v11, v187
	v_mov_b32_e32 v12, v188
	v_mov_b32_e32 v13, v189
	s_waitcnt lgkmcnt(0)
	v_sub_f32_e32 v19, v27, v10
	v_sub_f32_e32 v18, v26, v10
	v_sub_f32_e32 v21, v29, v10
	v_sub_f32_e32 v20, v28, v10
	v_pk_mul_f32 v[20:21], v[10:11], v[20:21] op_sel:[1,0]
	v_pk_mul_f32 v[10:11], v[10:11], v[18:19] op_sel:[1,0]
	v_pk_fma_f32 v[18:19], v[4:5], v[20:21], v[16:17]
	v_pk_fma_f32 v[10:11], v[2:3], v[10:11], v[14:15]
	v_pk_fma_f32 v[18:19], v[54:55], v[18:19], v[8:9]
	v_pk_fma_f32 v[10:11], v[56:57], v[10:11], v[6:7]
	s_nop 0
	v_cvt_pk_bf16_f32 v10, v10, v11
	v_cvt_pk_bf16_f32 v11, v18, v19
	v_sub_f32_e32 v19, v49, v12
	v_sub_f32_e32 v18, v48, v12
	global_store_dwordx2 v[128:129], v[10:11], off offset:32
	v_sub_f32_e32 v11, v47, v12
	v_sub_f32_e32 v10, v46, v12
	v_pk_mul_f32 v[18:19], v[12:13], v[18:19] op_sel:[1,0]
	v_pk_mul_f32 v[10:11], v[12:13], v[10:11] op_sel:[1,0]
	v_pk_fma_f32 v[12:13], v[4:5], v[18:19], v[16:17]
	v_mov_b32_e32 v18, v190
	v_mov_b32_e32 v19, v191
	v_pk_fma_f32 v[10:11], v[2:3], v[10:11], v[14:15]
	v_pk_fma_f32 v[12:13], v[54:55], v[12:13], v[8:9]
	v_pk_fma_f32 v[10:11], v[56:57], v[10:11], v[6:7]
	s_nop 0
	v_cvt_pk_bf16_f32 v10, v10, v11
	v_cvt_pk_bf16_f32 v11, v12, v13
	global_store_dwordx2 v[30:31], v[10:11], off offset:32
	s_waitcnt lgkmcnt(0)
	v_sub_f32_e32 v11, v67, v18
	v_sub_f32_e32 v10, v66, v18
	v_sub_f32_e32 v13, v69, v18
	v_sub_f32_e32 v12, v68, v18
	v_pk_mul_f32 v[12:13], v[18:19], v[12:13] op_sel:[1,0]
	v_pk_mul_f32 v[10:11], v[18:19], v[10:11] op_sel:[1,0]
	v_pk_fma_f32 v[4:5], v[4:5], v[12:13], v[16:17]
	v_pk_fma_f32 v[2:3], v[2:3], v[10:11], v[14:15]
	v_pk_fma_f32 v[4:5], v[54:55], v[4:5], v[8:9]
	v_pk_fma_f32 v[2:3], v[56:57], v[2:3], v[6:7]
	s_nop 0
	v_cvt_pk_bf16_f32 v2, v2, v3
	v_cvt_pk_bf16_f32 v3, v4, v5
	global_store_dwordx2 v[32:33], v[2:3], off offset:32
	s_and_saveexec_b64 s[0:1], vcc
	s_cbranch_execz .LBB0_595
	s_or_b32 s12, s4, 1
	s_ashr_i32 s13, s12, 31
	s_lshl_b64 s[12:13], s[12:13], 11
	v_lshl_add_u64 v[4:5], v[142:143], 0, s[12:13]
	global_store_dwordx2 v[4:5], v[2:3], off offset:32
; __device__ __forceinline__ unsigned pk2(float lo, float hi) { const f2_t v = {lo, hi}; return __builtin_bit_cast(unsigned, __builtin_convertvector(v, bf2_t)); }
;   __device__ __forceinline__ void operator()(f32x4 (&acc)[2][2][4][2], int pm, int pn, int wr_, int wc_, int fr_, int fq_, bf16_t* shm, int tid) const {
;     ...
;       for (int n = 0; n < 2; ++n) {
;         asm volatile("" ::: "memory");
;         const int col = pn * 256 + bj * 128 + wc * 32 + n * 16 + fq * 4;
;         const f32x4 gg = *(const f32x4*)(ng + col), bb = *(const f32x4*)(nb + col);
;         f32x4 sh = {0.f, 0.f, 0.f, 0.f}, sc = {0.f, 0.f, 0.f, 0.f};
;         if (!outp) { sh = *(const f32x4*)(msh + bio + col); sc = *(const f32x4*)(msc + bio + col); }
; #pragma unroll
;         for (int ai = 0; ai < 2; ++ai)
; #pragma unroll
;           for (int m = 0; m < 4; ++m) {
;             const int rl = ai * 128 + wr * 64 + m * 16 + fr, row = pm * 256 + rl;
;             const f2_t st = rst[rl];
;             f32x4 y = (acc[ai][bj][m][n] - st[0]) * st[1] * gg + bb;
;             if (outp) { *(f32x4*)(outp + (long)row * DM + col) = y; }
;             else {
;               y = y * (sc + 1.f) + sh;
;               u32x2 w; w.x = pk2(y[0], y[1]); w.y = pk2(y[2], y[3]);
;               *(u32x2*)(H + (long)row * DM + col) = w;
;               if (HA && (rl == 0 || rl == 255)) *(u32x2*)(HA + (long)(pm * 2 + (rl == 255)) * DM + col) = w;
;             }
;           }
.LBB0_595:
	s_or_b64 exec, exec, s[0:1]
	global_load_dwordx4 v[16:19], v[150:151], off offset:512
	global_load_dwordx4 v[2:5], v[144:145], off offset:512
	global_load_dwordx4 v[10:13], v[148:149], off offset:512
	global_load_dwordx4 v[6:9], v[146:147], off offset:512
	v_mov_b32_e32 v14, v176
	v_mov_b32_e32 v15, v177
	s_waitcnt lgkmcnt(0)
	v_sub_f32_e32 v21, v99, v14
	v_sub_f32_e32 v20, v98, v14
	v_sub_f32_e32 v27, v101, v14
	v_sub_f32_e32 v26, v100, v14
	v_pk_mul_f32 v[26:27], v[14:15], v[26:27] op_sel:[1,0]
	v_pk_mul_f32 v[20:21], v[14:15], v[20:21] op_sel:[1,0]
	s_waitcnt vmcnt(3)
	v_pk_add_f32 v[14:15], v[18:19], 1.0 op_sel_hi:[1,0]
	v_pk_add_f32 v[16:17], v[16:17], 1.0 op_sel_hi:[1,0]
	s_waitcnt vmcnt(1)
	v_pk_fma_f32 v[18:19], v[2:3], v[20:21], v[10:11]
	v_pk_fma_f32 v[20:21], v[4:5], v[26:27], v[12:13]
	s_waitcnt vmcnt(0)
	v_pk_fma_f32 v[18:19], v[16:17], v[18:19], v[6:7]
	v_pk_fma_f32 v[20:21], v[14:15], v[20:21], v[8:9]
	v_cvt_pk_bf16_f32 v18, v18, v19
	v_cvt_pk_bf16_f32 v19, v20, v21
	global_store_dwordx2 v[126:127], v[18:19], off offset:256
	s_and_saveexec_b64 s[0:1], s[6:7]
	s_cbranch_execz .LBB0_597
	s_ashr_i32 s5, s4, 31
	s_lshl_b64 s[12:13], s[4:5], 11
	v_lshl_add_u64 v[20:21], v[142:143], 0, s[12:13]
	global_store_dwordx2 v[20:21], v[18:19], off offset:256
.LBB0_597:
	s_or_b64 exec, exec, s[0:1]
	v_mov_b32_e32 v18, v178
	v_mov_b32_e32 v19, v179
	s_waitcnt lgkmcnt(0)
	v_sub_f32_e32 v21, v103, v18
	v_sub_f32_e32 v20, v102, v18
	v_sub_f32_e32 v27, v105, v18
	v_sub_f32_e32 v26, v104, v18
	v_pk_mul_f32 v[26:27], v[18:19], v[26:27] op_sel:[1,0]
	v_pk_mul_f32 v[18:19], v[18:19], v[20:21] op_sel:[1,0]
	v_pk_fma_f32 v[20:21], v[4:5], v[26:27], v[12:13]
	v_pk_fma_f32 v[18:19], v[2:3], v[18:19], v[10:11]
	v_pk_fma_f32 v[20:21], v[14:15], v[20:21], v[8:9]
	v_pk_fma_f32 v[18:19], v[16:17], v[18:19], v[6:7]
	s_nop 0
	v_cvt_pk_bf16_f32 v18, v18, v19
	v_cvt_pk_bf16_f32 v19, v20, v21
	global_store_dwordx2 v[110:111], v[18:19], off offset:256
	v_mov_b32_e32 v18, v180
	v_mov_b32_e32 v19, v181
	s_waitcnt lgkmcnt(0)
	v_sub_f32_e32 v21, v91, v18
	v_sub_f32_e32 v20, v90, v18
	v_sub_f32_e32 v27, v93, v18
	v_sub_f32_e32 v26, v92, v18
	v_pk_mul_f32 v[26:27], v[18:19], v[26:27] op_sel:[1,0]
	v_pk_mul_f32 v[18:19], v[18:19], v[20:21] op_sel:[1,0]
	v_pk_fma_f32 v[20:21], v[4:5], v[26:27], v[12:13]
	v_pk_fma_f32 v[18:19], v[2:3], v[18:19], v[10:11]
	v_pk_fma_f32 v[20:21], v[14:15], v[20:21], v[8:9]
	v_pk_fma_f32 v[18:19], v[16:17], v[18:19], v[6:7]
	s_nop 0
	v_cvt_pk_bf16_f32 v18, v18, v19
	v_cvt_pk_bf16_f32 v19, v20, v21
	global_store_dwordx2 v[94:95], v[18:19], off offset:256
	v_mov_b32_e32 v18, v182
	v_mov_b32_e32 v19, v183
	s_waitcnt lgkmcnt(0)
	v_sub_f32_e32 v21, v23, v18
	v_sub_f32_e32 v20, v22, v18
	v_sub_f32_e32 v23, v25, v18
	v_sub_f32_e32 v22, v24, v18
	v_pk_mul_f32 v[22:23], v[18:19], v[22:23] op_sel:[1,0]
	v_pk_mul_f32 v[18:19], v[18:19], v[20:21] op_sel:[1,0]
	v_pk_fma_f32 v[20:21], v[4:5], v[22:23], v[12:13]
	v_pk_fma_f32 v[18:19], v[2:3], v[18:19], v[10:11]
	v_pk_fma_f32 v[20:21], v[14:15], v[20:21], v[8:9]
	v_pk_fma_f32 v[18:19], v[16:17], v[18:19], v[6:7]
	s_nop 0
	v_cvt_pk_bf16_f32 v18, v18, v19
	v_cvt_pk_bf16_f32 v19, v20, v21
	global_store_dwordx2 v[96:97], v[18:19], off offset:256
	s_and_saveexec_b64 s[0:1], s[8:9]
	s_cbranch_execz .LBB0_599
	s_or_b32 s12, s4, 1
	s_ashr_i32 s13, s12, 31
	s_lshl_b64 s[12:13], s[12:13], 11
	v_lshl_add_u64 v[20:21], v[142:143], 0, s[12:13]
	global_store_dwordx2 v[20:21], v[18:19], off offset:256
.LBB0_599:
	s_or_b64 exec, exec, s[0:1]
	v_mov_b32_e32 v18, v184
	v_mov_b32_e32 v19, v185
	s_waitcnt lgkmcnt(0)
	v_sub_f32_e32 v21, v35, v18
	v_sub_f32_e32 v20, v34, v18
	v_sub_f32_e32 v23, v37, v18
	v_sub_f32_e32 v22, v36, v18
	v_pk_mul_f32 v[22:23], v[18:19], v[22:23] op_sel:[1,0]
	v_pk_mul_f32 v[18:19], v[18:19], v[20:21] op_sel:[1,0]
	v_pk_fma_f32 v[20:21], v[4:5], v[22:23], v[12:13]
	v_pk_fma_f32 v[18:19], v[2:3], v[18:19], v[10:11]
	v_pk_fma_f32 v[20:21], v[14:15], v[20:21], v[8:9]
	v_pk_fma_f32 v[18:19], v[16:17], v[18:19], v[6:7]
	s_nop 0
	v_cvt_pk_bf16_f32 v18, v18, v19
	v_cvt_pk_bf16_f32 v19, v20, v21
	global_store_dwordx2 v[112:113], v[18:19], off offset:256
	s_and_saveexec_b64 s[0:1], s[82:83]
	s_cbranch_execz .LBB0_601
	s_ashr_i32 s5, s4, 31
	s_lshl_b64 s[12:13], s[4:5], 11
	v_lshl_add_u64 v[20:21], v[142:143], 0, s[12:13]
	global_store_dwordx2 v[20:21], v[18:19], off offset:256
.LBB0_601:
	s_or_b64 exec, exec, s[0:1]
	v_mov_b32_e32 v18, v186
	v_mov_b32_e32 v19, v187
	v_mov_b32_e32 v20, v188
	v_mov_b32_e32 v21, v189
	s_waitcnt lgkmcnt(0)
	v_sub_f32_e32 v23, v43, v18
	v_sub_f32_e32 v22, v42, v18
	v_sub_f32_e32 v25, v45, v18
	v_sub_f32_e32 v24, v44, v18
	v_pk_mul_f32 v[24:25], v[18:19], v[24:25] op_sel:[1,0]
	v_pk_mul_f32 v[18:19], v[18:19], v[22:23] op_sel:[1,0]
	v_pk_fma_f32 v[22:23], v[4:5], v[24:25], v[12:13]
	v_pk_fma_f32 v[18:19], v[2:3], v[18:19], v[10:11]
	v_pk_fma_f32 v[22:23], v[14:15], v[22:23], v[8:9]
	v_pk_fma_f32 v[18:19], v[16:17], v[18:19], v[6:7]
	s_nop 0
	v_cvt_pk_bf16_f32 v18, v18, v19
	v_cvt_pk_bf16_f32 v19, v22, v23
	v_sub_f32_e32 v23, v65, v20
	v_sub_f32_e32 v22, v64, v20
	global_store_dwordx2 v[128:129], v[18:19], off offset:256
	v_sub_f32_e32 v19, v63, v20
	v_sub_f32_e32 v18, v62, v20
	v_pk_mul_f32 v[22:23], v[20:21], v[22:23] op_sel:[1,0]
	v_pk_mul_f32 v[18:19], v[20:21], v[18:19] op_sel:[1,0]
	v_pk_fma_f32 v[20:21], v[4:5], v[22:23], v[12:13]
	v_mov_b32_e32 v22, v190
	v_mov_b32_e32 v23, v191
	v_pk_fma_f32 v[18:19], v[2:3], v[18:19], v[10:11]
	v_pk_fma_f32 v[20:21], v[14:15], v[20:21], v[8:9]
	v_pk_fma_f32 v[18:19], v[16:17], v[18:19], v[6:7]
	s_nop 0
	v_cvt_pk_bf16_f32 v18, v18, v19
	v_cvt_pk_bf16_f32 v19, v20, v21
	global_store_dwordx2 v[30:31], v[18:19], off offset:256
	s_waitcnt lgkmcnt(0)
	v_sub_f32_e32 v19, v75, v22
	v_sub_f32_e32 v18, v74, v22
	v_sub_f32_e32 v21, v77, v22
	v_sub_f32_e32 v20, v76, v22
	v_pk_mul_f32 v[20:21], v[22:23], v[20:21] op_sel:[1,0]
	v_pk_mul_f32 v[18:19], v[22:23], v[18:19] op_sel:[1,0]
	v_pk_fma_f32 v[4:5], v[4:5], v[20:21], v[12:13]
	v_pk_fma_f32 v[2:3], v[2:3], v[18:19], v[10:11]
	v_pk_fma_f32 v[4:5], v[14:15], v[4:5], v[8:9]
	v_pk_fma_f32 v[2:3], v[16:17], v[2:3], v[6:7]
	s_nop 0
	v_cvt_pk_bf16_f32 v2, v2, v3
	v_cvt_pk_bf16_f32 v3, v4, v5
	global_store_dwordx2 v[32:33], v[2:3], off offset:256
	s_and_saveexec_b64 s[0:1], vcc
	s_cbranch_execz .LBB0_603
	s_or_b32 s12, s4, 1
	s_ashr_i32 s13, s12, 31
	s_lshl_b64 s[12:13], s[12:13], 11
	v_lshl_add_u64 v[4:5], v[142:143], 0, s[12:13]
	global_store_dwordx2 v[4:5], v[2:3], off offset:256
; __device__ __forceinline__ unsigned pk2(float lo, float hi) { const f2_t v = {lo, hi}; return __builtin_bit_cast(unsigned, __builtin_convertvector(v, bf2_t)); }
;   __device__ __forceinline__ void operator()(f32x4 (&acc)[2][2][4][2], int pm, int pn, int wr_, int wc_, int fr_, int fq_, bf16_t* shm, int tid) const {
;     ...
;       for (int n = 0; n < 2; ++n) {
;         asm volatile("" ::: "memory");
;         const int col = pn * 256 + bj * 128 + wc * 32 + n * 16 + fq * 4;
;         const f32x4 gg = *(const f32x4*)(ng + col), bb = *(const f32x4*)(nb + col);
;         f32x4 sh = {0.f, 0.f, 0.f, 0.f}, sc = {0.f, 0.f, 0.f, 0.f};
;         if (!outp) { sh = *(const f32x4*)(msh + bio + col); sc = *(const f32x4*)(msc + bio + col); }
; #pragma unroll
;         for (int ai = 0; ai < 2; ++ai)
; #pragma unroll
;           for (int m = 0; m < 4; ++m) {
;             const int rl = ai * 128 + wr * 64 + m * 16 + fr, row = pm * 256 + rl;
;             const f2_t st = rst[rl];
;             f32x4 y = (acc[ai][bj][m][n] - st[0]) * st[1] * gg + bb;
;             if (outp) { *(f32x4*)(outp + (long)row * DM + col) = y; }
;             else {
;               y = y * (sc + 1.f) + sh;
;               u32x2 w; w.x = pk2(y[0], y[1]); w.y = pk2(y[2], y[3]);
;               *(u32x2*)(H + (long)row * DM + col) = w;
;               if (HA && (rl == 0 || rl == 255)) *(u32x2*)(HA + (long)(pm * 2 + (rl == 255)) * DM + col) = w;
;             }
;           }
.LBB0_603:
	s_or_b64 exec, exec, s[0:1]
	global_load_dwordx4 v[16:19], v[150:151], off offset:576
	global_load_dwordx4 v[2:5], v[144:145], off offset:576
	global_load_dwordx4 v[10:13], v[148:149], off offset:576
	global_load_dwordx4 v[6:9], v[146:147], off offset:576
	v_mov_b32_e32 v14, v176
	v_mov_b32_e32 v15, v177
	s_waitcnt lgkmcnt(0)
	v_sub_f32_e32 v21, v115, v14
	v_sub_f32_e32 v20, v114, v14
	v_sub_f32_e32 v23, v117, v14
	v_sub_f32_e32 v22, v116, v14
	v_pk_mul_f32 v[22:23], v[14:15], v[22:23] op_sel:[1,0]
	v_pk_mul_f32 v[20:21], v[14:15], v[20:21] op_sel:[1,0]
	s_waitcnt vmcnt(3)
	v_pk_add_f32 v[14:15], v[18:19], 1.0 op_sel_hi:[1,0]
	v_pk_add_f32 v[16:17], v[16:17], 1.0 op_sel_hi:[1,0]
	s_waitcnt vmcnt(1)
	v_pk_fma_f32 v[18:19], v[2:3], v[20:21], v[10:11]
	v_pk_fma_f32 v[20:21], v[4:5], v[22:23], v[12:13]
	s_waitcnt vmcnt(0)
	v_pk_fma_f32 v[18:19], v[16:17], v[18:19], v[6:7]
	v_pk_fma_f32 v[20:21], v[14:15], v[20:21], v[8:9]
	v_cvt_pk_bf16_f32 v18, v18, v19
	v_cvt_pk_bf16_f32 v19, v20, v21
	global_store_dwordx2 v[126:127], v[18:19], off offset:288
	s_and_saveexec_b64 s[0:1], s[6:7]
	s_cbranch_execz .LBB0_605
	s_ashr_i32 s5, s4, 31
	s_lshl_b64 s[6:7], s[4:5], 11
	v_lshl_add_u64 v[20:21], v[142:143], 0, s[6:7]
	global_store_dwordx2 v[20:21], v[18:19], off offset:288
.LBB0_605:
	s_or_b64 exec, exec, s[0:1]
	v_mov_b32_e32 v18, v178
	v_mov_b32_e32 v19, v179
	s_waitcnt lgkmcnt(0)
	v_sub_f32_e32 v21, v119, v18
	v_sub_f32_e32 v20, v118, v18
	v_sub_f32_e32 v23, v121, v18
	v_sub_f32_e32 v22, v120, v18
	v_pk_mul_f32 v[22:23], v[18:19], v[22:23] op_sel:[1,0]
	v_pk_mul_f32 v[18:19], v[18:19], v[20:21] op_sel:[1,0]
	v_pk_fma_f32 v[20:21], v[4:5], v[22:23], v[12:13]
	v_pk_fma_f32 v[18:19], v[2:3], v[18:19], v[10:11]
	v_pk_fma_f32 v[20:21], v[14:15], v[20:21], v[8:9]
	v_pk_fma_f32 v[18:19], v[16:17], v[18:19], v[6:7]
	s_nop 0
	v_cvt_pk_bf16_f32 v18, v18, v19
	v_cvt_pk_bf16_f32 v19, v20, v21
	global_store_dwordx2 v[110:111], v[18:19], off offset:288
	v_mov_b32_e32 v18, v180
	v_mov_b32_e32 v19, v181
	s_waitcnt lgkmcnt(0)
	v_sub_f32_e32 v21, v107, v18
	v_sub_f32_e32 v20, v106, v18
	v_sub_f32_e32 v23, v109, v18
	v_sub_f32_e32 v22, v108, v18
	v_pk_mul_f32 v[22:23], v[18:19], v[22:23] op_sel:[1,0]
	v_pk_mul_f32 v[18:19], v[18:19], v[20:21] op_sel:[1,0]
	v_pk_fma_f32 v[20:21], v[4:5], v[22:23], v[12:13]
	v_pk_fma_f32 v[18:19], v[2:3], v[18:19], v[10:11]
	v_pk_fma_f32 v[20:21], v[14:15], v[20:21], v[8:9]
	v_pk_fma_f32 v[18:19], v[16:17], v[18:19], v[6:7]
	s_nop 0
	v_cvt_pk_bf16_f32 v18, v18, v19
	v_cvt_pk_bf16_f32 v19, v20, v21
	global_store_dwordx2 v[94:95], v[18:19], off offset:288
	v_mov_b32_e32 v18, v182
	v_mov_b32_e32 v19, v183
	s_waitcnt lgkmcnt(0)
	v_sub_f32_e32 v21, v39, v18
	v_sub_f32_e32 v20, v38, v18
	v_sub_f32_e32 v23, v41, v18
	v_sub_f32_e32 v22, v40, v18
	v_pk_mul_f32 v[22:23], v[18:19], v[22:23] op_sel:[1,0]
	v_pk_mul_f32 v[18:19], v[18:19], v[20:21] op_sel:[1,0]
	v_pk_fma_f32 v[20:21], v[4:5], v[22:23], v[12:13]
	v_pk_fma_f32 v[18:19], v[2:3], v[18:19], v[10:11]
	v_pk_fma_f32 v[20:21], v[14:15], v[20:21], v[8:9]
	v_pk_fma_f32 v[18:19], v[16:17], v[18:19], v[6:7]
	s_nop 0
	v_cvt_pk_bf16_f32 v18, v18, v19
	v_cvt_pk_bf16_f32 v19, v20, v21
	global_store_dwordx2 v[96:97], v[18:19], off offset:288
	s_and_saveexec_b64 s[0:1], s[8:9]
	s_cbranch_execz .LBB0_607
	s_or_b32 s6, s4, 1
	s_ashr_i32 s7, s6, 31
	s_lshl_b64 s[6:7], s[6:7], 11
	v_lshl_add_u64 v[20:21], v[142:143], 0, s[6:7]
	global_store_dwordx2 v[20:21], v[18:19], off offset:288
.LBB0_607:
	s_or_b64 exec, exec, s[0:1]
	v_mov_b32_e32 v18, v184
	v_mov_b32_e32 v19, v185
	s_waitcnt lgkmcnt(0)
	v_sub_f32_e32 v21, v51, v18
	v_sub_f32_e32 v20, v50, v18
	v_sub_f32_e32 v23, v53, v18
	v_sub_f32_e32 v22, v52, v18
	v_pk_mul_f32 v[22:23], v[18:19], v[22:23] op_sel:[1,0]
	v_pk_mul_f32 v[18:19], v[18:19], v[20:21] op_sel:[1,0]
	v_pk_fma_f32 v[20:21], v[4:5], v[22:23], v[12:13]
	v_pk_fma_f32 v[18:19], v[2:3], v[18:19], v[10:11]
	v_pk_fma_f32 v[20:21], v[14:15], v[20:21], v[8:9]
	v_pk_fma_f32 v[18:19], v[16:17], v[18:19], v[6:7]
	s_nop 0
	v_cvt_pk_bf16_f32 v18, v18, v19
	v_cvt_pk_bf16_f32 v19, v20, v21
	global_store_dwordx2 v[112:113], v[18:19], off offset:288
	s_and_saveexec_b64 s[0:1], s[82:83]
	s_cbranch_execz .LBB0_609
	s_ashr_i32 s5, s4, 31
	s_lshl_b64 s[6:7], s[4:5], 11
	v_lshl_add_u64 v[20:21], v[142:143], 0, s[6:7]
	global_store_dwordx2 v[20:21], v[18:19], off offset:288
.LBB0_609:
	s_or_b64 exec, exec, s[0:1]
	v_mov_b32_e32 v18, v186
	v_mov_b32_e32 v19, v187
	v_mov_b32_e32 v20, v188
	v_mov_b32_e32 v21, v189
	s_waitcnt lgkmcnt(0)
	v_sub_f32_e32 v23, v59, v18
	v_sub_f32_e32 v22, v58, v18
	v_sub_f32_e32 v25, v61, v18
	v_sub_f32_e32 v24, v60, v18
	v_pk_mul_f32 v[24:25], v[18:19], v[24:25] op_sel:[1,0]
	v_pk_mul_f32 v[18:19], v[18:19], v[22:23] op_sel:[1,0]
	v_pk_fma_f32 v[22:23], v[4:5], v[24:25], v[12:13]
	v_pk_fma_f32 v[18:19], v[2:3], v[18:19], v[10:11]
	v_pk_fma_f32 v[22:23], v[14:15], v[22:23], v[8:9]
	v_pk_fma_f32 v[18:19], v[16:17], v[18:19], v[6:7]
	s_nop 0
	v_cvt_pk_bf16_f32 v18, v18, v19
	v_cvt_pk_bf16_f32 v19, v22, v23
	v_sub_f32_e32 v23, v73, v20
	v_sub_f32_e32 v22, v72, v20
	global_store_dwordx2 v[128:129], v[18:19], off offset:288
	v_sub_f32_e32 v19, v71, v20
	v_sub_f32_e32 v18, v70, v20
	v_pk_mul_f32 v[22:23], v[20:21], v[22:23] op_sel:[1,0]
	v_pk_mul_f32 v[18:19], v[20:21], v[18:19] op_sel:[1,0]
	v_pk_fma_f32 v[20:21], v[4:5], v[22:23], v[12:13]
	v_mov_b32_e32 v22, v190
	v_mov_b32_e32 v23, v191
	v_pk_fma_f32 v[18:19], v[2:3], v[18:19], v[10:11]
	v_pk_fma_f32 v[20:21], v[14:15], v[20:21], v[8:9]
	v_pk_fma_f32 v[18:19], v[16:17], v[18:19], v[6:7]
	s_nop 0
	v_cvt_pk_bf16_f32 v18, v18, v19
	v_cvt_pk_bf16_f32 v19, v20, v21
	global_store_dwordx2 v[30:31], v[18:19], off offset:288
	s_waitcnt lgkmcnt(0)
	v_sub_f32_e32 v19, v123, v22
	v_sub_f32_e32 v18, v122, v22
	v_sub_f32_e32 v21, v125, v22
	v_sub_f32_e32 v20, v124, v22
	v_pk_mul_f32 v[20:21], v[22:23], v[20:21] op_sel:[1,0]
	v_pk_mul_f32 v[18:19], v[22:23], v[18:19] op_sel:[1,0]
	v_pk_fma_f32 v[4:5], v[4:5], v[20:21], v[12:13]
	v_pk_fma_f32 v[2:3], v[2:3], v[18:19], v[10:11]
	v_pk_fma_f32 v[4:5], v[14:15], v[4:5], v[8:9]
	v_pk_fma_f32 v[2:3], v[16:17], v[2:3], v[6:7]
	s_nop 0
	v_cvt_pk_bf16_f32 v2, v2, v3
	v_cvt_pk_bf16_f32 v3, v4, v5
	global_store_dwordx2 v[32:33], v[2:3], off offset:288
	s_and_saveexec_b64 s[0:1], vcc
	s_cbranch_execz .LBB0_468
	s_or_b32 s4, s4, 1
	s_ashr_i32 s5, s4, 31
	s_lshl_b64 s[4:5], s[4:5], 11
	v_lshl_add_u64 v[4:5], v[142:143], 0, s[4:5]
	global_store_dwordx2 v[4:5], v[2:3], off offset:288
	s_branch .LBB0_468
